# speedup vs baseline: 1.0141x; 1.0101x over previous
.LBB0_394:
	s_mov_b64 s[16:17], -1
	s_mov_b64 s[4:5], 0
	s_cmp_lt_i32 s90, 3
	s_mov_b64 s[34:35], 0
	s_cbranch_scc1 .LBB0_445
	s_cmp_gt_i32 s90, 4
	s_cbranch_scc0 .LBB0_435
	s_cmp_gt_i32 s90, 5
	s_cbranch_scc0 .LBB0_400
	s_cmp_eq_u32 s90, 6
	s_mov_b64 s[34:35], -1
	s_cbranch_scc0 .LBB0_399
	v_mov_b32_e32 v147, v195
	v_mov_b32_e32 v148, v193
	v_mov_b32_e32 v149, v194
	v_mov_b32_e32 v144, v165
	v_mul_f32_e32 v152, 0xbfb8aa3b, v123
	v_lshlrev_b32_e32 v145, 6, v147
	v_lshlrev_b32_e32 v150, 2, v147
	v_lshlrev_b32_e32 v147, 15, v149
	v_lshlrev_b32_e32 v146, 4, v148
	v_lshl_add_u32 v147, v148, 2, v147
	v_lshlrev_b32_e32 v148, 8, v144
	v_add3_u32 v151, v147, v148, s89
	v_mul_f32_e32 v147, 0xbfb8aa3b, v124
	v_mul_f32_e32 v148, 0xbfb8aa3b, v125
	v_exp_f32_e32 v147, v147
	v_exp_f32_e32 v148, v148
	v_lshl_add_u32 v145, v149, 8, v145
	v_mul_f32_e32 v149, 0xbfb8aa3b, v127
	v_add_f32_e32 v147, 1.0, v147
	v_add_f32_e32 v148, 1.0, v148
	v_rcp_f32_e32 v147, v147
	v_rcp_f32_e32 v148, v148
	v_exp_f32_e32 v149, v149
	v_exp_f32_e32 v152, v152
	v_mul_f32_e32 v147, 0x437f0000, v147
	v_mul_f32_e32 v148, 0x437f0000, v148
	v_cvt_rpi_i32_f32_e32 v147, v147
	v_cvt_rpi_i32_f32_e32 v148, v148
	v_add_f32_e32 v149, 1.0, v149
	v_rcp_f32_e32 v149, v149
	v_lshl_or_b32 v147, v148, 8, v147
	v_mul_f32_e32 v148, 0xbfb8aa3b, v126
	v_exp_f32_e32 v148, v148
	v_mul_f32_e32 v149, 0x437f0000, v149
	v_cvt_rpi_i32_f32_e32 v149, v149
	v_add_f32_e32 v148, 1.0, v148
	v_rcp_f32_e32 v148, v148
	v_add_f32_e32 v152, 1.0, v152
	v_min_u32_sdwa v149, v149, s81 dst_sel:BYTE_3 dst_unused:UNUSED_PAD src0_sel:DWORD src1_sel:DWORD
	v_rcp_f32_e32 v152, v152
	v_mul_f32_e32 v148, 0x437f0000, v148
	v_cvt_rpi_i32_f32_e32 v148, v148
	v_mul_f32_e32 v152, 0x437f0000, v152
	v_cvt_rpi_i32_f32_e32 v152, v152
	v_min_u32_sdwa v148, v148, s81 dst_sel:WORD_1 dst_unused:UNUSED_PAD src0_sel:DWORD src1_sel:DWORD
	v_mul_f32_e32 v153, 0xbfb8aa3b, v119
	v_or3_b32 v148, v147, v148, v149
	v_xor_b32_e32 v147, v150, v144
	v_lshl_add_u32 v147, v147, 4, v151
	ds_write_b32 v147, v148
	v_mul_f32_e32 v148, 0xbfb8aa3b, v120
	v_mul_f32_e32 v149, 0xbfb8aa3b, v121
	v_exp_f32_e32 v148, v148
	v_exp_f32_e32 v149, v149
	v_min_u32_sdwa v152, v152, s81 dst_sel:BYTE_3 dst_unused:UNUSED_PAD src0_sel:DWORD src1_sel:DWORD
	v_exp_f32_e32 v153, v153
	v_add_f32_e32 v148, 1.0, v148
	v_add_f32_e32 v149, 1.0, v149
	v_rcp_f32_e32 v148, v148
	v_rcp_f32_e32 v149, v149
	v_add_f32_e32 v153, 1.0, v153
	v_rcp_f32_e32 v153, v153
	v_mul_f32_e32 v148, 0x437f0000, v148
	v_mul_f32_e32 v149, 0x437f0000, v149
	v_cvt_rpi_i32_f32_e32 v148, v148
	v_cvt_rpi_i32_f32_e32 v149, v149
	v_mul_f32_e32 v153, 0x437f0000, v153
	v_lshl_or_b32 v148, v149, 8, v148
	v_mul_f32_e32 v149, 0xbfb8aa3b, v122
	v_exp_f32_e32 v149, v149
	v_cvt_rpi_i32_f32_e32 v153, v153
	v_mul_f32_e32 v154, 0xbfb8aa3b, v115
	v_exp_f32_e32 v154, v154
	v_add_f32_e32 v149, 1.0, v149
	v_rcp_f32_e32 v149, v149
	v_min_u32_sdwa v153, v153, s81 dst_sel:BYTE_3 dst_unused:UNUSED_PAD src0_sel:DWORD src1_sel:DWORD
	v_add_f32_e32 v154, 1.0, v154
	v_rcp_f32_e32 v154, v154
	v_mul_f32_e32 v149, 0x437f0000, v149
	v_cvt_rpi_i32_f32_e32 v149, v149
	v_mul_f32_e32 v154, 0x437f0000, v154
	v_cvt_rpi_i32_f32_e32 v154, v154
	v_min_u32_sdwa v149, v149, s81 dst_sel:WORD_1 dst_unused:UNUSED_PAD src0_sel:DWORD src1_sel:DWORD
	v_or3_b32 v145, v146, v145, v144
	v_or3_b32 v149, v148, v149, v152
	v_bitop3_b32 v148, v150, v144, 1 bitop3:0x36
	v_lshl_add_u32 v148, v148, 4, v151
	ds_write_b32 v148, v149
	v_mul_f32_e32 v149, 0xbfb8aa3b, v116
	v_mul_f32_e32 v152, 0xbfb8aa3b, v117
	v_exp_f32_e32 v149, v149
	v_exp_f32_e32 v152, v152
	v_min_u32_sdwa v154, v154, s81 dst_sel:BYTE_3 dst_unused:UNUSED_PAD src0_sel:DWORD src1_sel:DWORD
	v_lshlrev_b32_e32 v146, 4, v144
	v_add_f32_e32 v149, 1.0, v149
	v_add_f32_e32 v152, 1.0, v152
	v_rcp_f32_e32 v149, v149
	v_rcp_f32_e32 v152, v152
	s_and_b32 s17, s13, 0xffff
	s_mov_b32 s16, s12
	v_mul_f32_e32 v149, 0x437f0000, v149
	v_mul_f32_e32 v152, 0x437f0000, v152
	v_cvt_rpi_i32_f32_e32 v149, v149
	v_cvt_rpi_i32_f32_e32 v152, v152
	s_mov_b32 s18, s10
	s_mov_b32 s19, s11
	v_lshl_or_b32 v149, v152, 8, v149
	v_mul_f32_e32 v152, 0xbfb8aa3b, v118
	v_exp_f32_e32 v152, v152
	s_nop 0
	v_add_f32_e32 v152, 1.0, v152
	v_rcp_f32_e32 v152, v152
	s_nop 0
	v_mul_f32_e32 v152, 0x437f0000, v152
	v_cvt_rpi_i32_f32_e32 v152, v152
	v_min_u32_sdwa v152, v152, s81 dst_sel:WORD_1 dst_unused:UNUSED_PAD src0_sel:DWORD src1_sel:DWORD
	s_nop 0
	v_or3_b32 v152, v149, v152, v153
	v_bitop3_b32 v149, v150, v144, 2 bitop3:0x36
	v_lshl_add_u32 v149, v149, 4, v151
	ds_write_b32 v149, v152
	v_mul_f32_e32 v152, 0xbfb8aa3b, v112
	v_mul_f32_e32 v153, 0xbfb8aa3b, v113
	v_exp_f32_e32 v152, v152
	v_exp_f32_e32 v153, v153
	v_bitop3_b32 v150, v150, v144, 3 bitop3:0x36
	v_lshl_add_u32 v150, v150, 4, v151
	v_add_f32_e32 v152, 1.0, v152
	v_add_f32_e32 v153, 1.0, v153
	v_rcp_f32_e32 v152, v152
	v_rcp_f32_e32 v153, v153
	v_mul_f32_e32 v151, 0xbfb8aa3b, v108
	v_exp_f32_e32 v151, v151
	v_mul_f32_e32 v152, 0x437f0000, v152
	v_mul_f32_e32 v153, 0x437f0000, v153
	v_cvt_rpi_i32_f32_e32 v152, v152
	v_cvt_rpi_i32_f32_e32 v153, v153
	v_add_f32_e32 v151, 1.0, v151
	v_rcp_f32_e32 v151, v151
	v_lshl_or_b32 v152, v153, 8, v152
	v_mul_f32_e32 v153, 0xbfb8aa3b, v114
	v_exp_f32_e32 v153, v153
	v_mul_f32_e32 v151, 0x437f0000, v151
	v_cvt_rpi_i32_f32_e32 v151, v151
	v_add_f32_e32 v153, 1.0, v153
	v_rcp_f32_e32 v153, v153
	s_nop 0
	v_mul_f32_e32 v153, 0x437f0000, v153
	v_cvt_rpi_i32_f32_e32 v153, v153
	v_min_u32_sdwa v153, v153, s81 dst_sel:WORD_1 dst_unused:UNUSED_PAD src0_sel:DWORD src1_sel:DWORD
	s_nop 0
	v_or3_b32 v152, v152, v153, v154
	ds_write_b32 v150, v152
	v_mul_f32_e32 v152, 0xbfb8aa3b, v109
	v_exp_f32_e32 v152, v152
	v_mul_f32_e32 v153, 0xbfb8aa3b, v111
	v_exp_f32_e32 v153, v153
	v_add_f32_e32 v152, 1.0, v152
	v_rcp_f32_e32 v152, v152
	v_add_f32_e32 v153, 1.0, v153
	v_rcp_f32_e32 v153, v153
	v_mul_f32_e32 v152, 0x437f0000, v152
	v_cvt_rpi_i32_f32_e32 v152, v152
	v_mul_f32_e32 v153, 0x437f0000, v153
	v_cvt_rpi_i32_f32_e32 v153, v153
	v_lshl_or_b32 v151, v152, 8, v151
	v_mul_f32_e32 v152, 0xbfb8aa3b, v110
	v_exp_f32_e32 v152, v152
	v_min_u32_sdwa v153, v153, s81 dst_sel:BYTE_3 dst_unused:UNUSED_PAD src0_sel:DWORD src1_sel:DWORD
	v_add_f32_e32 v152, 1.0, v152
	v_rcp_f32_e32 v152, v152
	s_nop 0
	v_mul_f32_e32 v152, 0x437f0000, v152
	v_cvt_rpi_i32_f32_e32 v152, v152
	v_min_u32_sdwa v152, v152, s81 dst_sel:WORD_1 dst_unused:UNUSED_PAD src0_sel:DWORD src1_sel:DWORD
	s_nop 0
	v_or3_b32 v151, v151, v152, v153
	ds_write_b32 v147, v151 offset:4096
	v_mul_f32_e32 v151, 0xbfb8aa3b, v104
	v_mul_f32_e32 v152, 0xbfb8aa3b, v105
	v_exp_f32_e32 v151, v151
	v_exp_f32_e32 v152, v152
	v_mul_f32_e32 v153, 0xbfb8aa3b, v107
	v_exp_f32_e32 v153, v153
	v_add_f32_e32 v151, 1.0, v151
	v_add_f32_e32 v152, 1.0, v152
	v_rcp_f32_e32 v151, v151
	v_rcp_f32_e32 v152, v152
	v_add_f32_e32 v153, 1.0, v153
	v_rcp_f32_e32 v153, v153
	v_mul_f32_e32 v151, 0x437f0000, v151
	v_mul_f32_e32 v152, 0x437f0000, v152
	v_cvt_rpi_i32_f32_e32 v151, v151
	v_cvt_rpi_i32_f32_e32 v152, v152
	v_mul_f32_e32 v153, 0x437f0000, v153
	v_lshl_or_b32 v151, v152, 8, v151
	v_mul_f32_e32 v152, 0xbfb8aa3b, v106
	v_exp_f32_e32 v152, v152
	v_cvt_rpi_i32_f32_e32 v153, v153
	v_add_f32_e32 v152, 1.0, v152
	v_rcp_f32_e32 v152, v152
	v_min_u32_sdwa v153, v153, s81 dst_sel:BYTE_3 dst_unused:UNUSED_PAD src0_sel:DWORD src1_sel:DWORD
	v_mul_f32_e32 v152, 0x437f0000, v152
	v_cvt_rpi_i32_f32_e32 v152, v152
	v_min_u32_sdwa v152, v152, s81 dst_sel:WORD_1 dst_unused:UNUSED_PAD src0_sel:DWORD src1_sel:DWORD
	s_nop 0
	v_or3_b32 v151, v151, v152, v153
	ds_write_b32 v148, v151 offset:4096
	v_mul_f32_e32 v151, 0xbfb8aa3b, v100
	v_mul_f32_e32 v152, 0xbfb8aa3b, v101
	v_exp_f32_e32 v151, v151
	v_exp_f32_e32 v152, v152
	v_mul_f32_e32 v153, 0xbfb8aa3b, v103
	v_exp_f32_e32 v153, v153
	v_add_f32_e32 v151, 1.0, v151
	v_add_f32_e32 v152, 1.0, v152
	v_rcp_f32_e32 v151, v151
	v_rcp_f32_e32 v152, v152
	v_add_f32_e32 v153, 1.0, v153
	v_rcp_f32_e32 v153, v153
	v_mul_f32_e32 v151, 0x437f0000, v151
	v_mul_f32_e32 v152, 0x437f0000, v152
	v_cvt_rpi_i32_f32_e32 v151, v151
	v_cvt_rpi_i32_f32_e32 v152, v152
	v_mul_f32_e32 v153, 0x437f0000, v153
	v_lshl_or_b32 v151, v152, 8, v151
	v_mul_f32_e32 v152, 0xbfb8aa3b, v102
	v_exp_f32_e32 v152, v152
	v_cvt_rpi_i32_f32_e32 v153, v153
	v_add_f32_e32 v152, 1.0, v152
	v_rcp_f32_e32 v152, v152
	v_min_u32_sdwa v153, v153, s81 dst_sel:BYTE_3 dst_unused:UNUSED_PAD src0_sel:DWORD src1_sel:DWORD
	v_mul_f32_e32 v152, 0x437f0000, v152
	v_cvt_rpi_i32_f32_e32 v152, v152
	v_min_u32_sdwa v152, v152, s81 dst_sel:WORD_1 dst_unused:UNUSED_PAD src0_sel:DWORD src1_sel:DWORD
	s_nop 0
	v_or3_b32 v151, v151, v152, v153
	ds_write_b32 v149, v151 offset:4096
	v_mul_f32_e32 v151, 0xbfb8aa3b, v96
	v_mul_f32_e32 v152, 0xbfb8aa3b, v97
	v_exp_f32_e32 v151, v151
	v_exp_f32_e32 v152, v152
	v_mul_f32_e32 v153, 0xbfb8aa3b, v99
	v_exp_f32_e32 v153, v153
	v_add_f32_e32 v151, 1.0, v151
	v_add_f32_e32 v152, 1.0, v152
	v_rcp_f32_e32 v151, v151
	v_rcp_f32_e32 v152, v152
	v_add_f32_e32 v153, 1.0, v153
	v_rcp_f32_e32 v153, v153
	v_mul_f32_e32 v151, 0x437f0000, v151
	v_mul_f32_e32 v152, 0x437f0000, v152
	v_cvt_rpi_i32_f32_e32 v151, v151
	v_cvt_rpi_i32_f32_e32 v152, v152
	v_mul_f32_e32 v153, 0x437f0000, v153
	v_lshl_or_b32 v151, v152, 8, v151
	v_mul_f32_e32 v152, 0xbfb8aa3b, v98
	v_exp_f32_e32 v152, v152
	v_cvt_rpi_i32_f32_e32 v153, v153
	v_add_f32_e32 v152, 1.0, v152
	v_rcp_f32_e32 v152, v152
	v_min_u32_sdwa v153, v153, s81 dst_sel:BYTE_3 dst_unused:UNUSED_PAD src0_sel:DWORD src1_sel:DWORD
	v_mul_f32_e32 v152, 0x437f0000, v152
	v_cvt_rpi_i32_f32_e32 v152, v152
	v_min_u32_sdwa v152, v152, s81 dst_sel:WORD_1 dst_unused:UNUSED_PAD src0_sel:DWORD src1_sel:DWORD
	s_nop 0
	v_or3_b32 v151, v151, v152, v153
	ds_write_b32 v150, v151 offset:4096
	v_mul_f32_e32 v151, 0xbfb8aa3b, v92
	v_mul_f32_e32 v152, 0xbfb8aa3b, v93
	v_exp_f32_e32 v151, v151
	v_exp_f32_e32 v152, v152
	v_mul_f32_e32 v153, 0xbfb8aa3b, v95
	v_exp_f32_e32 v153, v153
	v_add_f32_e32 v151, 1.0, v151
	v_add_f32_e32 v152, 1.0, v152
	v_rcp_f32_e32 v151, v151
	v_rcp_f32_e32 v152, v152
	v_add_f32_e32 v153, 1.0, v153
	v_rcp_f32_e32 v153, v153
	v_mul_f32_e32 v151, 0x437f0000, v151
	v_mul_f32_e32 v152, 0x437f0000, v152
	v_cvt_rpi_i32_f32_e32 v151, v151
	v_cvt_rpi_i32_f32_e32 v152, v152
	v_mul_f32_e32 v153, 0x437f0000, v153
	v_lshl_or_b32 v151, v152, 8, v151
	v_mul_f32_e32 v152, 0xbfb8aa3b, v94
	v_exp_f32_e32 v152, v152
	v_cvt_rpi_i32_f32_e32 v153, v153
	v_add_f32_e32 v152, 1.0, v152
	v_rcp_f32_e32 v152, v152
	v_min_u32_sdwa v153, v153, s81 dst_sel:BYTE_3 dst_unused:UNUSED_PAD src0_sel:DWORD src1_sel:DWORD
	v_mul_f32_e32 v152, 0x437f0000, v152
	v_cvt_rpi_i32_f32_e32 v152, v152
	v_min_u32_sdwa v152, v152, s81 dst_sel:WORD_1 dst_unused:UNUSED_PAD src0_sel:DWORD src1_sel:DWORD
	s_nop 0
	v_or3_b32 v151, v151, v152, v153
	ds_write_b32 v147, v151 offset:8192
	v_mul_f32_e32 v151, 0xbfb8aa3b, v88
	v_mul_f32_e32 v152, 0xbfb8aa3b, v89
	v_exp_f32_e32 v151, v151
	v_exp_f32_e32 v152, v152
	v_mul_f32_e32 v153, 0xbfb8aa3b, v91
	v_exp_f32_e32 v153, v153
	v_add_f32_e32 v151, 1.0, v151
	v_add_f32_e32 v152, 1.0, v152
	v_rcp_f32_e32 v151, v151
	v_rcp_f32_e32 v152, v152
	v_add_f32_e32 v153, 1.0, v153
	v_rcp_f32_e32 v153, v153
	v_mul_f32_e32 v151, 0x437f0000, v151
	v_mul_f32_e32 v152, 0x437f0000, v152
	v_cvt_rpi_i32_f32_e32 v151, v151
	v_cvt_rpi_i32_f32_e32 v152, v152
	v_mul_f32_e32 v153, 0x437f0000, v153
	v_lshl_or_b32 v151, v152, 8, v151
	v_mul_f32_e32 v152, 0xbfb8aa3b, v90
	v_exp_f32_e32 v152, v152
	v_cvt_rpi_i32_f32_e32 v153, v153
	v_add_f32_e32 v152, 1.0, v152
	v_rcp_f32_e32 v152, v152
	v_min_u32_sdwa v153, v153, s81 dst_sel:BYTE_3 dst_unused:UNUSED_PAD src0_sel:DWORD src1_sel:DWORD
	v_mul_f32_e32 v152, 0x437f0000, v152
	v_cvt_rpi_i32_f32_e32 v152, v152
	v_min_u32_sdwa v152, v152, s81 dst_sel:WORD_1 dst_unused:UNUSED_PAD src0_sel:DWORD src1_sel:DWORD
	s_nop 0
	v_or3_b32 v151, v151, v152, v153
	ds_write_b32 v148, v151 offset:8192
	v_mul_f32_e32 v151, 0xbfb8aa3b, v84
	v_mul_f32_e32 v152, 0xbfb8aa3b, v85
	v_exp_f32_e32 v151, v151
	v_exp_f32_e32 v152, v152
	v_mul_f32_e32 v153, 0xbfb8aa3b, v87
	v_exp_f32_e32 v153, v153
	v_add_f32_e32 v151, 1.0, v151
	v_add_f32_e32 v152, 1.0, v152
	v_rcp_f32_e32 v151, v151
	v_rcp_f32_e32 v152, v152
	v_add_f32_e32 v153, 1.0, v153
	v_rcp_f32_e32 v153, v153
	v_mul_f32_e32 v151, 0x437f0000, v151
	v_mul_f32_e32 v152, 0x437f0000, v152
	v_cvt_rpi_i32_f32_e32 v151, v151
	v_cvt_rpi_i32_f32_e32 v152, v152
	v_mul_f32_e32 v153, 0x437f0000, v153
	v_lshl_or_b32 v151, v152, 8, v151
	v_mul_f32_e32 v152, 0xbfb8aa3b, v86
	v_exp_f32_e32 v152, v152
	v_cvt_rpi_i32_f32_e32 v153, v153
	v_add_f32_e32 v152, 1.0, v152
	v_rcp_f32_e32 v152, v152
	v_min_u32_sdwa v153, v153, s81 dst_sel:BYTE_3 dst_unused:UNUSED_PAD src0_sel:DWORD src1_sel:DWORD
	v_mul_f32_e32 v152, 0x437f0000, v152
	v_cvt_rpi_i32_f32_e32 v152, v152
	v_min_u32_sdwa v152, v152, s81 dst_sel:WORD_1 dst_unused:UNUSED_PAD src0_sel:DWORD src1_sel:DWORD
	s_nop 0
	v_or3_b32 v151, v151, v152, v153
	ds_write_b32 v149, v151 offset:8192
	v_mul_f32_e32 v151, 0xbfb8aa3b, v80
	v_mul_f32_e32 v152, 0xbfb8aa3b, v81
	v_exp_f32_e32 v151, v151
	v_exp_f32_e32 v152, v152
	v_mul_f32_e32 v153, 0xbfb8aa3b, v83
	v_exp_f32_e32 v153, v153
	v_add_f32_e32 v151, 1.0, v151
	v_add_f32_e32 v152, 1.0, v152
	v_rcp_f32_e32 v151, v151
	v_rcp_f32_e32 v152, v152
	v_add_f32_e32 v153, 1.0, v153
	v_rcp_f32_e32 v153, v153
	v_mul_f32_e32 v151, 0x437f0000, v151
	v_mul_f32_e32 v152, 0x437f0000, v152
	v_cvt_rpi_i32_f32_e32 v151, v151
	v_cvt_rpi_i32_f32_e32 v152, v152
	v_mul_f32_e32 v153, 0x437f0000, v153
	v_lshl_or_b32 v151, v152, 8, v151
	v_mul_f32_e32 v152, 0xbfb8aa3b, v82
	v_exp_f32_e32 v152, v152
	v_cvt_rpi_i32_f32_e32 v153, v153
	v_add_f32_e32 v152, 1.0, v152
	v_rcp_f32_e32 v152, v152
	v_min_u32_sdwa v153, v153, s81 dst_sel:BYTE_3 dst_unused:UNUSED_PAD src0_sel:DWORD src1_sel:DWORD
	v_mul_f32_e32 v152, 0x437f0000, v152
	v_cvt_rpi_i32_f32_e32 v152, v152
	v_min_u32_sdwa v152, v152, s81 dst_sel:WORD_1 dst_unused:UNUSED_PAD src0_sel:DWORD src1_sel:DWORD
	s_nop 0
	v_or3_b32 v151, v151, v152, v153
	ds_write_b32 v150, v151 offset:8192
	v_mul_f32_e32 v151, 0xbfb8aa3b, v76
	v_mul_f32_e32 v152, 0xbfb8aa3b, v77
	v_exp_f32_e32 v151, v151
	v_exp_f32_e32 v152, v152
	v_mul_f32_e32 v153, 0xbfb8aa3b, v79
	v_exp_f32_e32 v153, v153
	v_add_f32_e32 v151, 1.0, v151
	v_add_f32_e32 v152, 1.0, v152
	v_rcp_f32_e32 v151, v151
	v_rcp_f32_e32 v152, v152
	v_add_f32_e32 v153, 1.0, v153
	v_rcp_f32_e32 v153, v153
	v_mul_f32_e32 v151, 0x437f0000, v151
	v_mul_f32_e32 v152, 0x437f0000, v152
	v_cvt_rpi_i32_f32_e32 v151, v151
	v_cvt_rpi_i32_f32_e32 v152, v152
	v_mul_f32_e32 v153, 0x437f0000, v153
	v_lshl_or_b32 v151, v152, 8, v151
	v_mul_f32_e32 v152, 0xbfb8aa3b, v78
	v_exp_f32_e32 v152, v152
	v_cvt_rpi_i32_f32_e32 v153, v153
	v_add_f32_e32 v152, 1.0, v152
	v_rcp_f32_e32 v152, v152
	v_min_u32_sdwa v153, v153, s81 dst_sel:BYTE_3 dst_unused:UNUSED_PAD src0_sel:DWORD src1_sel:DWORD
	v_mul_f32_e32 v152, 0x437f0000, v152
	v_cvt_rpi_i32_f32_e32 v152, v152
	v_min_u32_sdwa v152, v152, s81 dst_sel:WORD_1 dst_unused:UNUSED_PAD src0_sel:DWORD src1_sel:DWORD
	s_nop 0
	v_or3_b32 v151, v151, v152, v153
	ds_write_b32 v147, v151 offset:12288
	v_mul_f32_e32 v151, 0xbfb8aa3b, v72
	v_mul_f32_e32 v152, 0xbfb8aa3b, v73
	v_exp_f32_e32 v151, v151
	v_exp_f32_e32 v152, v152
	v_mul_f32_e32 v153, 0xbfb8aa3b, v75
	v_exp_f32_e32 v153, v153
	v_add_f32_e32 v151, 1.0, v151
	v_add_f32_e32 v152, 1.0, v152
	v_rcp_f32_e32 v151, v151
	v_rcp_f32_e32 v152, v152
	v_add_f32_e32 v153, 1.0, v153
	v_rcp_f32_e32 v153, v153
	v_mul_f32_e32 v151, 0x437f0000, v151
	v_mul_f32_e32 v152, 0x437f0000, v152
	v_cvt_rpi_i32_f32_e32 v151, v151
	v_cvt_rpi_i32_f32_e32 v152, v152
	v_mul_f32_e32 v153, 0x437f0000, v153
	v_lshl_or_b32 v151, v152, 8, v151
	v_mul_f32_e32 v152, 0xbfb8aa3b, v74
	v_exp_f32_e32 v152, v152
	v_cvt_rpi_i32_f32_e32 v153, v153
	v_add_f32_e32 v152, 1.0, v152
	v_rcp_f32_e32 v152, v152
	v_min_u32_sdwa v153, v153, s81 dst_sel:BYTE_3 dst_unused:UNUSED_PAD src0_sel:DWORD src1_sel:DWORD
	v_mul_f32_e32 v152, 0x437f0000, v152
	v_cvt_rpi_i32_f32_e32 v152, v152
	v_min_u32_sdwa v152, v152, s81 dst_sel:WORD_1 dst_unused:UNUSED_PAD src0_sel:DWORD src1_sel:DWORD
	s_nop 0
	v_or3_b32 v151, v151, v152, v153
	ds_write_b32 v148, v151 offset:12288
	v_mul_f32_e32 v151, 0xbfb8aa3b, v68
	v_mul_f32_e32 v152, 0xbfb8aa3b, v69
	v_exp_f32_e32 v151, v151
	v_exp_f32_e32 v152, v152
	v_mul_f32_e32 v153, 0xbfb8aa3b, v71
	v_exp_f32_e32 v153, v153
	v_add_f32_e32 v151, 1.0, v151
	v_add_f32_e32 v152, 1.0, v152
	v_rcp_f32_e32 v151, v151
	v_rcp_f32_e32 v152, v152
	v_add_f32_e32 v153, 1.0, v153
	v_rcp_f32_e32 v153, v153
	v_mul_f32_e32 v151, 0x437f0000, v151
	v_mul_f32_e32 v152, 0x437f0000, v152
	v_cvt_rpi_i32_f32_e32 v151, v151
	v_cvt_rpi_i32_f32_e32 v152, v152
	v_mul_f32_e32 v153, 0x437f0000, v153
	v_lshl_or_b32 v151, v152, 8, v151
	v_mul_f32_e32 v152, 0xbfb8aa3b, v70
	v_exp_f32_e32 v152, v152
	v_cvt_rpi_i32_f32_e32 v153, v153
	v_add_f32_e32 v152, 1.0, v152
	v_rcp_f32_e32 v152, v152
	v_min_u32_sdwa v153, v153, s81 dst_sel:BYTE_3 dst_unused:UNUSED_PAD src0_sel:DWORD src1_sel:DWORD
	v_mul_f32_e32 v152, 0x437f0000, v152
	v_cvt_rpi_i32_f32_e32 v152, v152
	v_min_u32_sdwa v152, v152, s81 dst_sel:WORD_1 dst_unused:UNUSED_PAD src0_sel:DWORD src1_sel:DWORD
	s_nop 0
	v_or3_b32 v151, v151, v152, v153
	ds_write_b32 v149, v151 offset:12288
	v_mul_f32_e32 v151, 0xbfb8aa3b, v64
	v_mul_f32_e32 v152, 0xbfb8aa3b, v65
	v_exp_f32_e32 v151, v151
	v_exp_f32_e32 v152, v152
	v_mul_f32_e32 v153, 0xbfb8aa3b, v67
	v_exp_f32_e32 v153, v153
	v_add_f32_e32 v151, 1.0, v151
	v_add_f32_e32 v152, 1.0, v152
	v_rcp_f32_e32 v151, v151
	v_rcp_f32_e32 v152, v152
	v_add_f32_e32 v153, 1.0, v153
	v_rcp_f32_e32 v153, v153
	v_mul_f32_e32 v151, 0x437f0000, v151
	v_mul_f32_e32 v152, 0x437f0000, v152
	v_cvt_rpi_i32_f32_e32 v151, v151
	v_cvt_rpi_i32_f32_e32 v152, v152
	v_mul_f32_e32 v153, 0x437f0000, v153
	v_lshl_or_b32 v151, v152, 8, v151
	v_mul_f32_e32 v152, 0xbfb8aa3b, v66
	v_exp_f32_e32 v152, v152
	v_cvt_rpi_i32_f32_e32 v153, v153
	v_add_f32_e32 v152, 1.0, v152
	v_rcp_f32_e32 v152, v152
	v_min_u32_sdwa v153, v153, s81 dst_sel:BYTE_3 dst_unused:UNUSED_PAD src0_sel:DWORD src1_sel:DWORD
	v_mul_f32_e32 v152, 0x437f0000, v152
	v_cvt_rpi_i32_f32_e32 v152, v152
	v_min_u32_sdwa v152, v152, s81 dst_sel:WORD_1 dst_unused:UNUSED_PAD src0_sel:DWORD src1_sel:DWORD
	s_nop 0
	v_or3_b32 v151, v151, v152, v153
	ds_write_b32 v150, v151 offset:12288
	v_mul_f32_e32 v151, 0xbfb8aa3b, v60
	v_mul_f32_e32 v152, 0xbfb8aa3b, v61
	v_exp_f32_e32 v151, v151
	v_exp_f32_e32 v152, v152
	v_mul_f32_e32 v153, 0xbfb8aa3b, v63
	v_exp_f32_e32 v153, v153
	v_add_f32_e32 v151, 1.0, v151
	v_add_f32_e32 v152, 1.0, v152
	v_rcp_f32_e32 v151, v151
	v_rcp_f32_e32 v152, v152
	v_add_f32_e32 v153, 1.0, v153
	v_rcp_f32_e32 v153, v153
	v_mul_f32_e32 v151, 0x437f0000, v151
	v_mul_f32_e32 v152, 0x437f0000, v152
	v_cvt_rpi_i32_f32_e32 v151, v151
	v_cvt_rpi_i32_f32_e32 v152, v152
	v_mul_f32_e32 v153, 0x437f0000, v153
	v_lshl_or_b32 v151, v152, 8, v151
	v_mul_f32_e32 v152, 0xbfb8aa3b, v62
	v_exp_f32_e32 v152, v152
	v_cvt_rpi_i32_f32_e32 v153, v153
	v_add_f32_e32 v152, 1.0, v152
	v_rcp_f32_e32 v152, v152
	v_min_u32_sdwa v153, v153, s81 dst_sel:BYTE_3 dst_unused:UNUSED_PAD src0_sel:DWORD src1_sel:DWORD
	v_mul_f32_e32 v152, 0x437f0000, v152
	v_cvt_rpi_i32_f32_e32 v152, v152
	v_min_u32_sdwa v152, v152, s81 dst_sel:WORD_1 dst_unused:UNUSED_PAD src0_sel:DWORD src1_sel:DWORD
	s_nop 0
	v_or3_b32 v151, v151, v152, v153
	ds_write_b32 v147, v151 offset:16384
	v_mul_f32_e32 v151, 0xbfb8aa3b, v56
	v_mul_f32_e32 v152, 0xbfb8aa3b, v57
	v_exp_f32_e32 v151, v151
	v_exp_f32_e32 v152, v152
	v_mul_f32_e32 v153, 0xbfb8aa3b, v59
	v_exp_f32_e32 v153, v153
	v_add_f32_e32 v151, 1.0, v151
	v_add_f32_e32 v152, 1.0, v152
	v_rcp_f32_e32 v151, v151
	v_rcp_f32_e32 v152, v152
	v_add_f32_e32 v153, 1.0, v153
	v_rcp_f32_e32 v153, v153
	v_mul_f32_e32 v151, 0x437f0000, v151
	v_mul_f32_e32 v152, 0x437f0000, v152
	v_cvt_rpi_i32_f32_e32 v151, v151
	v_cvt_rpi_i32_f32_e32 v152, v152
	v_mul_f32_e32 v153, 0x437f0000, v153
	v_lshl_or_b32 v151, v152, 8, v151
	v_mul_f32_e32 v152, 0xbfb8aa3b, v58
	v_exp_f32_e32 v152, v152
	v_cvt_rpi_i32_f32_e32 v153, v153
	v_add_f32_e32 v152, 1.0, v152
	v_rcp_f32_e32 v152, v152
	v_min_u32_sdwa v153, v153, s81 dst_sel:BYTE_3 dst_unused:UNUSED_PAD src0_sel:DWORD src1_sel:DWORD
	v_mul_f32_e32 v152, 0x437f0000, v152
	v_cvt_rpi_i32_f32_e32 v152, v152
	v_min_u32_sdwa v152, v152, s81 dst_sel:WORD_1 dst_unused:UNUSED_PAD src0_sel:DWORD src1_sel:DWORD
	s_nop 0
	v_or3_b32 v151, v151, v152, v153
	ds_write_b32 v148, v151 offset:16384
	v_mul_f32_e32 v151, 0xbfb8aa3b, v52
	v_mul_f32_e32 v152, 0xbfb8aa3b, v53
	v_exp_f32_e32 v151, v151
	v_exp_f32_e32 v152, v152
	v_mul_f32_e32 v153, 0xbfb8aa3b, v55
	v_exp_f32_e32 v153, v153
	v_add_f32_e32 v151, 1.0, v151
	v_add_f32_e32 v152, 1.0, v152
	v_rcp_f32_e32 v151, v151
	v_rcp_f32_e32 v152, v152
	v_add_f32_e32 v153, 1.0, v153
	v_rcp_f32_e32 v153, v153
	v_mul_f32_e32 v151, 0x437f0000, v151
	v_mul_f32_e32 v152, 0x437f0000, v152
	v_cvt_rpi_i32_f32_e32 v151, v151
	v_cvt_rpi_i32_f32_e32 v152, v152
	v_mul_f32_e32 v153, 0x437f0000, v153
	v_lshl_or_b32 v151, v152, 8, v151
	v_mul_f32_e32 v152, 0xbfb8aa3b, v54
	v_exp_f32_e32 v152, v152
	v_cvt_rpi_i32_f32_e32 v153, v153
	v_add_f32_e32 v152, 1.0, v152
	v_rcp_f32_e32 v152, v152
	v_min_u32_sdwa v153, v153, s81 dst_sel:BYTE_3 dst_unused:UNUSED_PAD src0_sel:DWORD src1_sel:DWORD
	v_mul_f32_e32 v152, 0x437f0000, v152
	v_cvt_rpi_i32_f32_e32 v152, v152
	v_min_u32_sdwa v152, v152, s81 dst_sel:WORD_1 dst_unused:UNUSED_PAD src0_sel:DWORD src1_sel:DWORD
	s_nop 0
	v_or3_b32 v151, v151, v152, v153
	ds_write_b32 v149, v151 offset:16384
	v_mul_f32_e32 v151, 0xbfb8aa3b, v48
	v_mul_f32_e32 v152, 0xbfb8aa3b, v49
	v_exp_f32_e32 v151, v151
	v_exp_f32_e32 v152, v152
	v_mul_f32_e32 v153, 0xbfb8aa3b, v51
	v_exp_f32_e32 v153, v153
	v_add_f32_e32 v151, 1.0, v151
	v_add_f32_e32 v152, 1.0, v152
	v_rcp_f32_e32 v151, v151
	v_rcp_f32_e32 v152, v152
	v_add_f32_e32 v153, 1.0, v153
	v_rcp_f32_e32 v153, v153
	v_mul_f32_e32 v151, 0x437f0000, v151
	v_mul_f32_e32 v152, 0x437f0000, v152
	v_cvt_rpi_i32_f32_e32 v151, v151
	v_cvt_rpi_i32_f32_e32 v152, v152
	v_mul_f32_e32 v153, 0x437f0000, v153
	v_lshl_or_b32 v151, v152, 8, v151
	v_mul_f32_e32 v152, 0xbfb8aa3b, v50
	v_exp_f32_e32 v152, v152
	v_cvt_rpi_i32_f32_e32 v153, v153
	v_add_f32_e32 v152, 1.0, v152
	v_rcp_f32_e32 v152, v152
	v_min_u32_sdwa v153, v153, s81 dst_sel:BYTE_3 dst_unused:UNUSED_PAD src0_sel:DWORD src1_sel:DWORD
	v_mul_f32_e32 v152, 0x437f0000, v152
	v_cvt_rpi_i32_f32_e32 v152, v152
	v_min_u32_sdwa v152, v152, s81 dst_sel:WORD_1 dst_unused:UNUSED_PAD src0_sel:DWORD src1_sel:DWORD
	s_nop 0
	v_or3_b32 v151, v151, v152, v153
	ds_write_b32 v150, v151 offset:16384
	v_mul_f32_e32 v151, 0xbfb8aa3b, v44
	v_mul_f32_e32 v152, 0xbfb8aa3b, v45
	v_exp_f32_e32 v151, v151
	v_exp_f32_e32 v152, v152
	v_mul_f32_e32 v153, 0xbfb8aa3b, v47
	v_exp_f32_e32 v153, v153
	v_add_f32_e32 v151, 1.0, v151
	v_add_f32_e32 v152, 1.0, v152
	v_rcp_f32_e32 v151, v151
	v_rcp_f32_e32 v152, v152
	v_add_f32_e32 v153, 1.0, v153
	v_rcp_f32_e32 v153, v153
	v_mul_f32_e32 v151, 0x437f0000, v151
	v_mul_f32_e32 v152, 0x437f0000, v152
	v_cvt_rpi_i32_f32_e32 v151, v151
	v_cvt_rpi_i32_f32_e32 v152, v152
	v_mul_f32_e32 v153, 0x437f0000, v153
	v_lshl_or_b32 v151, v152, 8, v151
	v_mul_f32_e32 v152, 0xbfb8aa3b, v46
	v_exp_f32_e32 v152, v152
	v_cvt_rpi_i32_f32_e32 v153, v153
	v_add_f32_e32 v152, 1.0, v152
	v_rcp_f32_e32 v152, v152
	v_min_u32_sdwa v153, v153, s81 dst_sel:BYTE_3 dst_unused:UNUSED_PAD src0_sel:DWORD src1_sel:DWORD
	v_mul_f32_e32 v152, 0x437f0000, v152
	v_cvt_rpi_i32_f32_e32 v152, v152
	v_min_u32_sdwa v152, v152, s81 dst_sel:WORD_1 dst_unused:UNUSED_PAD src0_sel:DWORD src1_sel:DWORD
	s_nop 0
	v_or3_b32 v151, v151, v152, v153
	ds_write_b32 v147, v151 offset:20480
	v_mul_f32_e32 v151, 0xbfb8aa3b, v40
	v_mul_f32_e32 v152, 0xbfb8aa3b, v41
	v_exp_f32_e32 v151, v151
	v_exp_f32_e32 v152, v152
	v_mul_f32_e32 v153, 0xbfb8aa3b, v43
	v_exp_f32_e32 v153, v153
	v_add_f32_e32 v151, 1.0, v151
	v_add_f32_e32 v152, 1.0, v152
	v_rcp_f32_e32 v151, v151
	v_rcp_f32_e32 v152, v152
	v_add_f32_e32 v153, 1.0, v153
	v_rcp_f32_e32 v153, v153
	v_mul_f32_e32 v151, 0x437f0000, v151
	v_mul_f32_e32 v152, 0x437f0000, v152
	v_cvt_rpi_i32_f32_e32 v151, v151
	v_cvt_rpi_i32_f32_e32 v152, v152
	v_mul_f32_e32 v153, 0x437f0000, v153
	v_lshl_or_b32 v151, v152, 8, v151
	v_mul_f32_e32 v152, 0xbfb8aa3b, v42
	v_exp_f32_e32 v152, v152
	v_cvt_rpi_i32_f32_e32 v153, v153
	v_add_f32_e32 v152, 1.0, v152
	v_rcp_f32_e32 v152, v152
	v_min_u32_sdwa v153, v153, s81 dst_sel:BYTE_3 dst_unused:UNUSED_PAD src0_sel:DWORD src1_sel:DWORD
	v_mul_f32_e32 v152, 0x437f0000, v152
	v_cvt_rpi_i32_f32_e32 v152, v152
	v_min_u32_sdwa v152, v152, s81 dst_sel:WORD_1 dst_unused:UNUSED_PAD src0_sel:DWORD src1_sel:DWORD
	s_nop 0
	v_or3_b32 v151, v151, v152, v153
	ds_write_b32 v148, v151 offset:20480
	v_mul_f32_e32 v151, 0xbfb8aa3b, v36
	v_mul_f32_e32 v152, 0xbfb8aa3b, v37
	v_exp_f32_e32 v151, v151
	v_exp_f32_e32 v152, v152
	v_mul_f32_e32 v153, 0xbfb8aa3b, v39
	v_exp_f32_e32 v153, v153
	v_add_f32_e32 v151, 1.0, v151
	v_add_f32_e32 v152, 1.0, v152
	v_rcp_f32_e32 v151, v151
	v_rcp_f32_e32 v152, v152
	v_add_f32_e32 v153, 1.0, v153
	v_rcp_f32_e32 v153, v153
	v_mul_f32_e32 v151, 0x437f0000, v151
	v_mul_f32_e32 v152, 0x437f0000, v152
	v_cvt_rpi_i32_f32_e32 v151, v151
	v_cvt_rpi_i32_f32_e32 v152, v152
	v_mul_f32_e32 v153, 0x437f0000, v153
	v_lshl_or_b32 v151, v152, 8, v151
	v_mul_f32_e32 v152, 0xbfb8aa3b, v38
	v_exp_f32_e32 v152, v152
	v_cvt_rpi_i32_f32_e32 v153, v153
	v_add_f32_e32 v152, 1.0, v152
	v_rcp_f32_e32 v152, v152
	v_min_u32_sdwa v153, v153, s81 dst_sel:BYTE_3 dst_unused:UNUSED_PAD src0_sel:DWORD src1_sel:DWORD
	v_mul_f32_e32 v152, 0x437f0000, v152
	v_cvt_rpi_i32_f32_e32 v152, v152
	v_min_u32_sdwa v152, v152, s81 dst_sel:WORD_1 dst_unused:UNUSED_PAD src0_sel:DWORD src1_sel:DWORD
	s_nop 0
	v_or3_b32 v151, v151, v152, v153
	ds_write_b32 v149, v151 offset:20480
	v_mul_f32_e32 v151, 0xbfb8aa3b, v32
	v_mul_f32_e32 v152, 0xbfb8aa3b, v33
	v_exp_f32_e32 v151, v151
	v_exp_f32_e32 v152, v152
	v_mul_f32_e32 v153, 0xbfb8aa3b, v35
	v_exp_f32_e32 v153, v153
	v_add_f32_e32 v151, 1.0, v151
	v_add_f32_e32 v152, 1.0, v152
	v_rcp_f32_e32 v151, v151
	v_rcp_f32_e32 v152, v152
	v_add_f32_e32 v153, 1.0, v153
	v_rcp_f32_e32 v153, v153
	v_mul_f32_e32 v151, 0x437f0000, v151
	v_mul_f32_e32 v152, 0x437f0000, v152
	v_cvt_rpi_i32_f32_e32 v151, v151
	v_cvt_rpi_i32_f32_e32 v152, v152
	v_mul_f32_e32 v153, 0x437f0000, v153
	v_lshl_or_b32 v151, v152, 8, v151
	v_mul_f32_e32 v152, 0xbfb8aa3b, v34
	v_exp_f32_e32 v152, v152
	v_cvt_rpi_i32_f32_e32 v153, v153
	v_add_f32_e32 v152, 1.0, v152
	v_rcp_f32_e32 v152, v152
	v_min_u32_sdwa v153, v153, s81 dst_sel:BYTE_3 dst_unused:UNUSED_PAD src0_sel:DWORD src1_sel:DWORD
	v_mul_f32_e32 v152, 0x437f0000, v152
	v_cvt_rpi_i32_f32_e32 v152, v152
	v_min_u32_sdwa v152, v152, s81 dst_sel:WORD_1 dst_unused:UNUSED_PAD src0_sel:DWORD src1_sel:DWORD
	s_nop 0
	v_or3_b32 v151, v151, v152, v153
	ds_write_b32 v150, v151 offset:20480
	v_mul_f32_e32 v151, 0xbfb8aa3b, v28
	v_mul_f32_e32 v152, 0xbfb8aa3b, v29
	v_exp_f32_e32 v151, v151
	v_exp_f32_e32 v152, v152
	v_mul_f32_e32 v153, 0xbfb8aa3b, v31
	v_exp_f32_e32 v153, v153
	v_add_f32_e32 v151, 1.0, v151
	v_add_f32_e32 v152, 1.0, v152
	v_rcp_f32_e32 v151, v151
	v_rcp_f32_e32 v152, v152
	v_add_f32_e32 v153, 1.0, v153
	v_rcp_f32_e32 v153, v153
	v_mul_f32_e32 v151, 0x437f0000, v151
	v_mul_f32_e32 v152, 0x437f0000, v152
	v_cvt_rpi_i32_f32_e32 v151, v151
	v_cvt_rpi_i32_f32_e32 v152, v152
	v_mul_f32_e32 v153, 0x437f0000, v153
	v_lshl_or_b32 v151, v152, 8, v151
	v_mul_f32_e32 v152, 0xbfb8aa3b, v30
	v_exp_f32_e32 v152, v152
	v_cvt_rpi_i32_f32_e32 v153, v153
	v_add_f32_e32 v152, 1.0, v152
	v_rcp_f32_e32 v152, v152
	v_min_u32_sdwa v153, v153, s81 dst_sel:BYTE_3 dst_unused:UNUSED_PAD src0_sel:DWORD src1_sel:DWORD
	v_mul_f32_e32 v152, 0x437f0000, v152
	v_cvt_rpi_i32_f32_e32 v152, v152
	v_min_u32_sdwa v152, v152, s81 dst_sel:WORD_1 dst_unused:UNUSED_PAD src0_sel:DWORD src1_sel:DWORD
	s_nop 0
	v_or3_b32 v151, v151, v152, v153
	ds_write_b32 v147, v151 offset:24576
	v_mul_f32_e32 v151, 0xbfb8aa3b, v24
	v_mul_f32_e32 v152, 0xbfb8aa3b, v25
	v_exp_f32_e32 v151, v151
	v_exp_f32_e32 v152, v152
	v_mul_f32_e32 v153, 0xbfb8aa3b, v27
	v_exp_f32_e32 v153, v153
	v_add_f32_e32 v151, 1.0, v151
	v_add_f32_e32 v152, 1.0, v152
	v_rcp_f32_e32 v151, v151
	v_rcp_f32_e32 v152, v152
	v_add_f32_e32 v153, 1.0, v153
	v_rcp_f32_e32 v153, v153
	v_mul_f32_e32 v151, 0x437f0000, v151
	v_mul_f32_e32 v152, 0x437f0000, v152
	v_cvt_rpi_i32_f32_e32 v151, v151
	v_cvt_rpi_i32_f32_e32 v152, v152
	v_mul_f32_e32 v153, 0x437f0000, v153
	v_lshl_or_b32 v151, v152, 8, v151
	v_mul_f32_e32 v152, 0xbfb8aa3b, v26
	v_exp_f32_e32 v152, v152
	v_cvt_rpi_i32_f32_e32 v153, v153
	v_add_f32_e32 v152, 1.0, v152
	v_rcp_f32_e32 v152, v152
	v_min_u32_sdwa v153, v153, s81 dst_sel:BYTE_3 dst_unused:UNUSED_PAD src0_sel:DWORD src1_sel:DWORD
	v_mul_f32_e32 v152, 0x437f0000, v152
	v_cvt_rpi_i32_f32_e32 v152, v152
	v_min_u32_sdwa v152, v152, s81 dst_sel:WORD_1 dst_unused:UNUSED_PAD src0_sel:DWORD src1_sel:DWORD
	s_nop 0
	v_or3_b32 v151, v151, v152, v153
	ds_write_b32 v148, v151 offset:24576
	v_mul_f32_e32 v151, 0xbfb8aa3b, v20
	v_mul_f32_e32 v152, 0xbfb8aa3b, v21
	v_exp_f32_e32 v151, v151
	v_exp_f32_e32 v152, v152
	v_mul_f32_e32 v153, 0xbfb8aa3b, v23
	v_exp_f32_e32 v153, v153
	v_add_f32_e32 v151, 1.0, v151
	v_add_f32_e32 v152, 1.0, v152
	v_rcp_f32_e32 v151, v151
	v_rcp_f32_e32 v152, v152
	v_add_f32_e32 v153, 1.0, v153
	v_rcp_f32_e32 v153, v153
	v_mul_f32_e32 v151, 0x437f0000, v151
	v_mul_f32_e32 v152, 0x437f0000, v152
	v_cvt_rpi_i32_f32_e32 v151, v151
	v_cvt_rpi_i32_f32_e32 v152, v152
	v_mul_f32_e32 v153, 0x437f0000, v153
	v_lshl_or_b32 v151, v152, 8, v151
	v_mul_f32_e32 v152, 0xbfb8aa3b, v22
	v_exp_f32_e32 v152, v152
	v_cvt_rpi_i32_f32_e32 v153, v153
	v_add_f32_e32 v152, 1.0, v152
	v_rcp_f32_e32 v152, v152
	v_min_u32_sdwa v153, v153, s81 dst_sel:BYTE_3 dst_unused:UNUSED_PAD src0_sel:DWORD src1_sel:DWORD
	v_mul_f32_e32 v152, 0x437f0000, v152
	v_cvt_rpi_i32_f32_e32 v152, v152
	v_min_u32_sdwa v152, v152, s81 dst_sel:WORD_1 dst_unused:UNUSED_PAD src0_sel:DWORD src1_sel:DWORD
	s_nop 0
	v_or3_b32 v151, v151, v152, v153
	ds_write_b32 v149, v151 offset:24576
	v_mul_f32_e32 v151, 0xbfb8aa3b, v16
	v_mul_f32_e32 v152, 0xbfb8aa3b, v17
	v_exp_f32_e32 v151, v151
	v_exp_f32_e32 v152, v152
	v_mul_f32_e32 v153, 0xbfb8aa3b, v19
	v_exp_f32_e32 v153, v153
	v_add_f32_e32 v151, 1.0, v151
	v_add_f32_e32 v152, 1.0, v152
	v_rcp_f32_e32 v151, v151
	v_rcp_f32_e32 v152, v152
	v_add_f32_e32 v153, 1.0, v153
	v_rcp_f32_e32 v153, v153
	v_mul_f32_e32 v151, 0x437f0000, v151
	v_mul_f32_e32 v152, 0x437f0000, v152
	v_cvt_rpi_i32_f32_e32 v151, v151
	v_cvt_rpi_i32_f32_e32 v152, v152
	v_mul_f32_e32 v153, 0x437f0000, v153
	v_lshl_or_b32 v151, v152, 8, v151
	v_mul_f32_e32 v152, 0xbfb8aa3b, v18
	v_exp_f32_e32 v152, v152
	v_cvt_rpi_i32_f32_e32 v153, v153
	v_add_f32_e32 v152, 1.0, v152
	v_rcp_f32_e32 v152, v152
	v_min_u32_sdwa v153, v153, s81 dst_sel:BYTE_3 dst_unused:UNUSED_PAD src0_sel:DWORD src1_sel:DWORD
	v_mul_f32_e32 v152, 0x437f0000, v152
	v_cvt_rpi_i32_f32_e32 v152, v152
	v_min_u32_sdwa v152, v152, s81 dst_sel:WORD_1 dst_unused:UNUSED_PAD src0_sel:DWORD src1_sel:DWORD
	s_nop 0
	v_or3_b32 v151, v151, v152, v153
	ds_write_b32 v150, v151 offset:24576
	v_mul_f32_e32 v151, 0xbfb8aa3b, v12
	v_mul_f32_e32 v152, 0xbfb8aa3b, v13
	v_exp_f32_e32 v151, v151
	v_exp_f32_e32 v152, v152
	v_mul_f32_e32 v153, 0xbfb8aa3b, v15
	v_exp_f32_e32 v153, v153
	v_add_f32_e32 v151, 1.0, v151
	v_add_f32_e32 v152, 1.0, v152
	v_rcp_f32_e32 v151, v151
	v_rcp_f32_e32 v152, v152
	v_add_f32_e32 v153, 1.0, v153
	v_rcp_f32_e32 v153, v153
	v_mul_f32_e32 v151, 0x437f0000, v151
	v_mul_f32_e32 v152, 0x437f0000, v152
	v_cvt_rpi_i32_f32_e32 v151, v151
	v_cvt_rpi_i32_f32_e32 v152, v152
	v_mul_f32_e32 v153, 0x437f0000, v153
	v_lshl_or_b32 v151, v152, 8, v151
	v_mul_f32_e32 v152, 0xbfb8aa3b, v14
	v_exp_f32_e32 v152, v152
	v_cvt_rpi_i32_f32_e32 v153, v153
	v_add_f32_e32 v152, 1.0, v152
	v_rcp_f32_e32 v152, v152
	v_min_u32_sdwa v153, v153, s81 dst_sel:BYTE_3 dst_unused:UNUSED_PAD src0_sel:DWORD src1_sel:DWORD
	v_mul_f32_e32 v152, 0x437f0000, v152
	v_cvt_rpi_i32_f32_e32 v152, v152
	v_min_u32_sdwa v152, v152, s81 dst_sel:WORD_1 dst_unused:UNUSED_PAD src0_sel:DWORD src1_sel:DWORD
	s_nop 0
	v_or3_b32 v151, v151, v152, v153
	ds_write_b32 v147, v151 offset:28672
	v_mul_f32_e32 v147, 0xbfb8aa3b, v8
	v_mul_f32_e32 v151, 0xbfb8aa3b, v9
	v_exp_f32_e32 v147, v147
	v_exp_f32_e32 v151, v151
	v_mul_f32_e32 v152, 0xbfb8aa3b, v11
	v_exp_f32_e32 v152, v152
	v_add_f32_e32 v147, 1.0, v147
	v_add_f32_e32 v151, 1.0, v151
	v_rcp_f32_e32 v147, v147
	v_rcp_f32_e32 v151, v151
	v_add_f32_e32 v152, 1.0, v152
	v_rcp_f32_e32 v152, v152
	v_mul_f32_e32 v147, 0x437f0000, v147
	v_mul_f32_e32 v151, 0x437f0000, v151
	v_cvt_rpi_i32_f32_e32 v147, v147
	v_cvt_rpi_i32_f32_e32 v151, v151
	v_mul_f32_e32 v152, 0x437f0000, v152
	v_lshl_or_b32 v147, v151, 8, v147
	v_mul_f32_e32 v151, 0xbfb8aa3b, v10
	v_exp_f32_e32 v151, v151
	v_cvt_rpi_i32_f32_e32 v152, v152
	v_add_f32_e32 v151, 1.0, v151
	v_rcp_f32_e32 v151, v151
	v_min_u32_sdwa v152, v152, s81 dst_sel:BYTE_3 dst_unused:UNUSED_PAD src0_sel:DWORD src1_sel:DWORD
	v_mul_f32_e32 v151, 0x437f0000, v151
	v_cvt_rpi_i32_f32_e32 v151, v151
	v_min_u32_sdwa v151, v151, s81 dst_sel:WORD_1 dst_unused:UNUSED_PAD src0_sel:DWORD src1_sel:DWORD
	s_nop 0
	v_or3_b32 v147, v147, v151, v152
	ds_write_b32 v148, v147 offset:28672
	v_mul_f32_e32 v147, 0xbfb8aa3b, v4
	v_mul_f32_e32 v148, 0xbfb8aa3b, v5
	v_exp_f32_e32 v147, v147
	v_exp_f32_e32 v148, v148
	v_mul_f32_e32 v151, 0xbfb8aa3b, v7
	v_exp_f32_e32 v151, v151
	v_add_f32_e32 v147, 1.0, v147
	v_add_f32_e32 v148, 1.0, v148
	v_rcp_f32_e32 v147, v147
	v_rcp_f32_e32 v148, v148
	v_add_f32_e32 v151, 1.0, v151
	v_rcp_f32_e32 v151, v151
	v_mul_f32_e32 v147, 0x437f0000, v147
	v_mul_f32_e32 v148, 0x437f0000, v148
	v_cvt_rpi_i32_f32_e32 v147, v147
	v_cvt_rpi_i32_f32_e32 v148, v148
	v_mul_f32_e32 v151, 0x437f0000, v151
	v_lshl_or_b32 v147, v148, 8, v147
	v_mul_f32_e32 v148, 0xbfb8aa3b, v6
	v_exp_f32_e32 v148, v148
	v_cvt_rpi_i32_f32_e32 v151, v151
	v_add_f32_e32 v148, 1.0, v148
	v_rcp_f32_e32 v148, v148
	v_min_u32_sdwa v151, v151, s81 dst_sel:BYTE_3 dst_unused:UNUSED_PAD src0_sel:DWORD src1_sel:DWORD
	v_mul_f32_e32 v148, 0x437f0000, v148
	v_cvt_rpi_i32_f32_e32 v148, v148
	v_min_u32_sdwa v148, v148, s81 dst_sel:WORD_1 dst_unused:UNUSED_PAD src0_sel:DWORD src1_sel:DWORD
	s_nop 0
	v_or3_b32 v147, v147, v148, v151
	ds_write_b32 v149, v147 offset:28672
	v_mul_f32_e32 v147, 0xbfb8aa3b, v0
	v_mul_f32_e32 v148, 0xbfb8aa3b, v1
	v_exp_f32_e32 v147, v147
	v_exp_f32_e32 v148, v148
	v_mul_f32_e32 v149, 0xbfb8aa3b, v3
	v_exp_f32_e32 v149, v149
	v_add_f32_e32 v147, 1.0, v147
	v_add_f32_e32 v148, 1.0, v148
	v_rcp_f32_e32 v147, v147
	v_rcp_f32_e32 v148, v148
	v_add_f32_e32 v149, 1.0, v149
	v_rcp_f32_e32 v149, v149
	v_mul_f32_e32 v147, 0x437f0000, v147
	v_mul_f32_e32 v148, 0x437f0000, v148
	v_cvt_rpi_i32_f32_e32 v147, v147
	v_cvt_rpi_i32_f32_e32 v148, v148
	v_mul_f32_e32 v149, 0x437f0000, v149
	v_lshl_or_b32 v147, v148, 8, v147
	v_mul_f32_e32 v148, 0xbfb8aa3b, v2
	v_exp_f32_e32 v148, v148
	v_cvt_rpi_i32_f32_e32 v149, v149
	v_ashrrev_i32_e32 v151, 4, v145
	v_add_f32_e32 v148, 1.0, v148
	v_rcp_f32_e32 v148, v148
	v_min_u32_sdwa v149, v149, s81 dst_sel:BYTE_3 dst_unused:UNUSED_PAD src0_sel:DWORD src1_sel:DWORD
	v_mul_f32_e32 v148, 0x437f0000, v148
	v_cvt_rpi_i32_f32_e32 v148, v148
	v_min_u32_sdwa v148, v148, s81 dst_sel:WORD_1 dst_unused:UNUSED_PAD src0_sel:DWORD src1_sel:DWORD
	s_nop 0
	v_or3_b32 v147, v147, v148, v149
	ds_write_b32 v150, v147 offset:28672
	v_and_b32_e32 v150, 0xf0, v146
	v_xor_b32_e32 v146, v151, v144
	v_lshlrev_b32_e32 v146, 4, v146
	v_and_b32_e32 v146, 0xf0, v146
	v_lshl_or_b32 v146, v151, 8, v146
	v_add_u32_e32 v146, 0x10000, v146
	s_waitcnt lgkmcnt(0)
	s_barrier
	s_waitcnt vmcnt(0)
	ds_read_b128 v[146:149], v146
	v_mad_u64_u32 v[152:153], s[34:35], v151, s33, v[150:151]
	s_waitcnt lgkmcnt(0)
	buffer_store_dwordx4 v[146:149], v152, s[16:19], 0 offen sc1
	s_nop 1
	v_add_u32_e32 v146, 0x200, v145
	v_ashrrev_i32_e32 v151, 4, v146
	v_xor_b32_e32 v146, v151, v144
	v_lshlrev_b32_e32 v146, 4, v146
	v_and_b32_e32 v146, 0xf0, v146
	v_lshl_or_b32 v146, v151, 8, v146
	v_add_u32_e32 v146, 0x10000, v146
	ds_read_b128 v[146:149], v146
	v_mad_u64_u32 v[152:153], s[34:35], v151, s33, v[150:151]
	s_waitcnt lgkmcnt(0)
	buffer_store_dwordx4 v[146:149], v152, s[16:19], 0 offen sc1
	s_nop 1
	v_add_u32_e32 v146, 0x400, v145
	v_ashrrev_i32_e32 v151, 4, v146
	v_xor_b32_e32 v146, v151, v144
	v_lshlrev_b32_e32 v146, 4, v146
	v_and_b32_e32 v146, 0xf0, v146
	v_lshl_or_b32 v146, v151, 8, v146
	v_add_u32_e32 v146, 0x10000, v146
	ds_read_b128 v[146:149], v146
	v_mad_u64_u32 v[152:153], s[34:35], v151, s33, v[150:151]
	s_waitcnt lgkmcnt(0)
	buffer_store_dwordx4 v[146:149], v152, s[16:19], 0 offen sc1
	s_nop 1
	v_add_u32_e32 v146, 0x600, v145
	v_ashrrev_i32_e32 v151, 4, v146
	v_xor_b32_e32 v146, v151, v144
	v_lshlrev_b32_e32 v146, 4, v146
	v_and_b32_e32 v146, 0xf0, v146
	v_lshl_or_b32 v146, v151, 8, v146
	v_add_u32_e32 v146, 0x10000, v146
	ds_read_b128 v[146:149], v146
	v_mad_u64_u32 v[152:153], s[34:35], v151, s33, v[150:151]
	s_waitcnt lgkmcnt(0)
	buffer_store_dwordx4 v[146:149], v152, s[16:19], 0 offen sc1
	s_nop 1
	v_add_u32_e32 v146, 0x800, v145
	v_ashrrev_i32_e32 v151, 4, v146
	v_xor_b32_e32 v146, v151, v144
	v_lshlrev_b32_e32 v146, 4, v146
	v_and_b32_e32 v146, 0xf0, v146
	v_lshl_or_b32 v146, v151, 8, v146
	v_add_u32_e32 v146, 0x10000, v146
	ds_read_b128 v[146:149], v146
	v_mad_u64_u32 v[152:153], s[34:35], v151, s33, v[150:151]
	s_waitcnt lgkmcnt(0)
	buffer_store_dwordx4 v[146:149], v152, s[16:19], 0 offen sc1
	s_nop 1
	v_add_u32_e32 v146, 0xa00, v145
	v_ashrrev_i32_e32 v151, 4, v146
	v_xor_b32_e32 v146, v151, v144
	v_lshlrev_b32_e32 v146, 4, v146
	v_and_b32_e32 v146, 0xf0, v146
	v_lshl_or_b32 v146, v151, 8, v146
	v_add_u32_e32 v146, 0x10000, v146
	ds_read_b128 v[146:149], v146
	v_mad_u64_u32 v[152:153], s[34:35], v151, s33, v[150:151]
	s_waitcnt lgkmcnt(0)
	buffer_store_dwordx4 v[146:149], v152, s[16:19], 0 offen sc1
	s_nop 1
	v_add_u32_e32 v146, 0xc00, v145
	v_ashrrev_i32_e32 v151, 4, v146
	v_xor_b32_e32 v146, v151, v144
	v_lshlrev_b32_e32 v146, 4, v146
	v_and_b32_e32 v146, 0xf0, v146
	v_lshl_or_b32 v146, v151, 8, v146
	v_add_u32_e32 v146, 0x10000, v146
	ds_read_b128 v[146:149], v146
	v_mad_u64_u32 v[152:153], s[34:35], v151, s33, v[150:151]
	v_add_u32_e32 v145, 0xe00, v145
	s_waitcnt lgkmcnt(0)
	buffer_store_dwordx4 v[146:149], v152, s[16:19], 0 offen sc1
	s_nop 1
	v_ashrrev_i32_e32 v148, 4, v145
	v_xor_b32_e32 v144, v148, v144
	v_lshlrev_b32_e32 v144, 4, v144
	v_and_b32_e32 v144, 0xf0, v144
	v_lshl_or_b32 v144, v148, 8, v144
	v_add_u32_e32 v144, 0x10000, v144
	ds_read_b128 v[144:147], v144
	v_mad_u64_u32 v[148:149], s[34:35], v148, s33, v[150:151]
	s_mov_b64 s[34:35], 0
	s_waitcnt lgkmcnt(0)
	buffer_store_dwordx4 v[144:147], v148, s[16:19], 0 offen sc1
	s_waitcnt lgkmcnt(0)
	s_barrier

.LBB0_457:
	v_mov_b32_e32 v156, v194
	v_mov_b32_e32 v157, v165
	v_mov_b32_e32 v158, v195
	v_mov_b32_e32 v159, v193
	v_lshlrev_b32_e32 v202, 16, v142
	v_lshlrev_b32_e32 v144, 4, v158
	v_lshl_add_u32 v144, v159, 2, v144
	v_ashrrev_i32_e32 v145, 31, v144
	v_lshlrev_b64 v[148:149], 2, v[144:145]
	v_lshl_add_u64 v[152:153], s[66:67], 0, v[148:149]
	v_lshl_add_u64 v[154:155], s[64:65], 0, v[148:149]
	global_load_dwordx4 v[144:147], v[152:153], off
	global_load_dwordx4 v[148:151], v[154:155], off
	v_and_b32_e32 v246, 63, v163
	v_lshlrev_b32_e32 v246, 2, v246
	global_load_dword v247, v246, s[68:69] offset:256
	global_load_dword v246, v246, s[68:69]
	v_and_b32_e32 v203, 0xffff0000, v142
	v_lshlrev_b32_e32 v142, 6, v158
	v_lshl_add_u32 v158, v158, 2, v159
	v_lshlrev_b32_e32 v160, 15, v156
	v_lshl_add_u32 v142, v156, 8, v142
	v_xor_b32_e32 v156, v158, v157
	v_lshl_or_b32 v201, v159, 4, v142
	v_lshlrev_b32_e32 v142, 4, v156
	v_lshlrev_b32_e32 v198, 8, v157
	v_add3_u32 v142, v142, v160, s89
	v_add_u32_e32 v158, v142, v198
	v_lshlrev_b32_e32 v196, 16, v140
	v_and_b32_e32 v197, 0xffff0000, v140
	v_lshlrev_b32_e32 v140, 16, v141
	v_and_b32_e32 v141, 0xffff0000, v141
	v_or_b32_e32 v156, v201, v157
	s_movk_i32 s4, 0x100
	v_add_u32_e32 v200, 0x100, v156
	v_cmp_gt_i32_e64 s[4:5], s4, v156
	s_and_b32 s9, s9, 0xffff
	v_cmp_lt_i32_e32 vcc, s81, v156
	s_waitcnt vmcnt(0)
	v_add_f32_e32 v142, v124, v144
	v_add_f32_e32 v159, v120, v148
	v_add_f32_e32 v160, v125, v145
	v_add_f32_e32 v198, v121, v149
	v_add_f32_e32 v199, v126, v146
	v_add_f32_e32 v204, v122, v150
	v_add_f32_e32 v205, v127, v147
	v_add_f32_e32 v206, v123, v151
	v_med3_f32 v142, v142, s6, v191
	v_med3_f32 v159, v159, s6, v191
	v_med3_f32 v160, v160, s6, v191
	v_med3_f32 v198, v198, s6, v191
	v_med3_f32 v199, v199, s6, v191
	v_med3_f32 v204, v204, s6, v191
	v_med3_f32 v205, v205, s6, v191
	v_med3_f32 v206, v206, s6, v191
	v_mul_f32_e32 v142, 0xbfb8aa3b, v142
	v_mul_f32_e32 v159, 0xbfb8aa3b, v159
	v_mul_f32_e32 v160, 0xbfb8aa3b, v160
	v_mul_f32_e32 v207, 0xbfb8aa3b, v198
	v_mul_f32_e32 v208, 0xbfb8aa3b, v199
	v_mul_f32_e32 v209, 0xbfb8aa3b, v204
	v_mul_f32_e32 v205, 0xbfb8aa3b, v205
	v_mul_f32_e32 v206, 0xbfb8aa3b, v206
	v_exp_f32_e32 v198, v142
	v_exp_f32_e32 v142, v159
	v_exp_f32_e32 v199, v160
	v_exp_f32_e32 v159, v207
	v_exp_f32_e32 v204, v208
	v_exp_f32_e32 v160, v209
	v_exp_f32_e32 v205, v205
	v_exp_f32_e32 v206, v206
	v_add_f32_e32 v142, 1.0, v142
	v_add_f32_e32 v159, 1.0, v159
	v_pk_add_f32 v[198:199], v[198:199], 1.0 op_sel_hi:[1,0]
	v_add_f32_e32 v160, 1.0, v160
	v_add_f32_e32 v211, 1.0, v206
	v_pk_add_f32 v[204:205], v[204:205], 1.0 op_sel_hi:[1,0]
	v_mul_f32_e32 v206, v198, v142
	v_mul_f32_e32 v207, v199, v159
	v_mul_f32_e32 v208, v204, v160
	v_mul_f32_e32 v209, v205, v211
	v_rcp_f32_e32 v206, v206
	v_rcp_f32_e32 v207, v207
	v_rcp_f32_e32 v208, v208
	v_rcp_f32_e32 v209, v209
	v_mul_f32_e32 v142, v142, v206
	v_pk_mul_f32 v[198:199], v[198:199], v[206:207]
	v_mul_f32_e32 v160, v160, v208
	v_pk_mul_f32 v[204:205], v[204:205], v[208:209]
	v_mul_f32_e32 v206, v211, v209
	v_pk_mul_f32 v[196:197], v[198:199], v[196:197]
	v_mul_f32_e32 v160, 0x437f0000, v160
	v_pk_mul_f32 v[140:141], v[204:205], v[140:141]
	v_mul_f32_e32 v198, 0x437f0000, v206
	v_rndne_f32_e32 v160, v160
	v_cvt_pk_f16_f32 v140, v140, v141
	v_rndne_f32_e32 v141, v198
	v_cvt_f16_f32_e32 v141, v141
	v_cvt_f16_f32_e32 v160, v160
	v_mul_f32_e32 v159, v159, v207
	v_mul_f32_e32 v159, 0x437f0000, v159
	v_bfi_b32 v199, s98, v141, v140
	v_pack_b32_f16 v198, v160, v140
	v_add_f32_e32 v140, v104, v148
	v_rndne_f32_e32 v159, v159
	v_med3_f32 v140, v140, s6, v191
	v_mul_f32_e32 v140, 0xbfb8aa3b, v140
	v_cvt_f16_f32_e32 v159, v159
	v_exp_f32_e32 v141, v140
	v_mul_f32_e32 v142, 0x437f0000, v142
	v_rndne_f32_e32 v142, v142
	v_cvt_pk_f16_f32 v196, v196, v197
	v_add_f32_e32 v210, v108, v144
	v_bfi_b32 v197, s98, v159, v196
	v_add_f32_e32 v159, 1.0, v141
	v_add_f32_e32 v141, v109, v145
	v_cvt_f16_f32_e32 v142, v142
	v_med3_f32 v140, v210, s6, v191
	v_med3_f32 v141, v141, s6, v191
	v_mul_f32_e32 v140, 0xbfb8aa3b, v140
	v_mul_f32_e32 v141, 0xbfb8aa3b, v141
	v_exp_f32_e32 v140, v140
	v_exp_f32_e32 v141, v141
	v_pack_b32_f16 v196, v142, v196
	v_add_f32_e32 v142, v105, v149
	v_med3_f32 v142, v142, s6, v191
	v_mul_f32_e32 v142, 0xbfb8aa3b, v142
	v_pk_add_f32 v[140:141], v[140:141], 1.0 op_sel_hi:[1,0]
	v_exp_f32_e32 v160, v142
	v_mul_f32_e32 v142, v140, v159
	v_rcp_f32_e32 v142, v142
	ds_write_b128 v158, v[196:199]
	v_lshlrev_b32_e32 v196, 16, v143
	v_and_b32_e32 v197, 0xffff0000, v143
	v_add_f32_e32 v160, 1.0, v160
	v_mul_f32_e32 v143, v159, v142
	v_mul_f32_e32 v159, 0x437f0000, v143
	v_mul_f32_e32 v143, v141, v160
	v_rcp_f32_e32 v143, v143
	v_rndne_f32_e32 v159, v159
	v_cvt_f16_f32_e32 v159, v159
	v_pk_mul_f32 v[140:141], v[140:141], v[142:143]
	v_add_f32_e32 v142, v107, v151
	v_pk_mul_f32 v[140:141], v[140:141], v[202:203]
	v_med3_f32 v142, v142, s6, v191
	v_cvt_pk_f16_f32 v198, v140, v141
	v_add_f32_e32 v141, v106, v150
	v_med3_f32 v141, v141, s6, v191
	v_mul_f32_e32 v141, 0xbfb8aa3b, v141
	v_exp_f32_e32 v141, v141
	v_mul_f32_e32 v140, v160, v143
	v_mul_f32_e32 v140, 0x437f0000, v140
	v_rndne_f32_e32 v143, v140
	v_add_f32_e32 v140, v110, v146
	v_add_f32_e32 v160, 1.0, v141
	v_add_f32_e32 v141, v111, v147
	v_med3_f32 v140, v140, s6, v191
	v_med3_f32 v141, v141, s6, v191
	v_mul_f32_e32 v140, 0xbfb8aa3b, v140
	v_mul_f32_e32 v141, 0xbfb8aa3b, v141
	v_exp_f32_e32 v140, v140
	v_exp_f32_e32 v141, v141
	v_mul_f32_e32 v142, 0xbfb8aa3b, v142
	v_exp_f32_e32 v199, v142
	v_pk_add_f32 v[140:141], v[140:141], 1.0 op_sel_hi:[1,0]
	v_cvt_f16_f32_e32 v202, v143
	v_mul_f32_e32 v142, v140, v160
	v_rcp_f32_e32 v142, v142
	v_add_f32_e32 v199, 1.0, v199
	v_mul_f32_e32 v143, v160, v142
	v_mul_f32_e32 v160, 0x437f0000, v143
	v_mul_f32_e32 v143, v141, v199
	v_rcp_f32_e32 v143, v143
	v_rndne_f32_e32 v160, v160
	v_cvt_f16_f32_e32 v160, v160
	v_mul_f32_e32 v199, v199, v143
	v_mul_f32_e32 v199, 0x437f0000, v199
	v_rndne_f32_e32 v199, v199
	v_cvt_f16_f32_e32 v199, v199
	v_pk_mul_f32 v[140:141], v[140:141], v[142:143]
	s_nop 0
	v_pk_mul_f32 v[140:141], v[140:141], v[196:197]
	v_lshlrev_b32_e32 v196, 16, v137
	v_cvt_pk_f16_f32 v140, v140, v141
	v_bfi_b32 v143, s98, v199, v140
	v_bfi_b32 v141, s98, v202, v198
	v_pack_b32_f16 v142, v160, v140
	v_pack_b32_f16 v140, v159, v198
	ds_write_b128 v158, v[140:143] offset:4096
	v_add_f32_e32 v142, v88, v148
	v_lshlrev_b32_e32 v140, 16, v136
	v_and_b32_e32 v141, 0xffff0000, v136
	v_add_f32_e32 v136, v92, v144
	v_med3_f32 v142, v142, s6, v191
	v_mul_f32_e32 v142, 0xbfb8aa3b, v142
	v_med3_f32 v136, v136, s6, v191
	v_exp_f32_e32 v143, v142
	v_mul_f32_e32 v136, 0xbfb8aa3b, v136
	v_exp_f32_e32 v142, v136
	v_add_f32_e32 v136, v93, v145
	v_med3_f32 v136, v136, s6, v191
	v_mul_f32_e32 v136, 0xbfb8aa3b, v136
	v_add_f32_e32 v159, 1.0, v143
	v_exp_f32_e32 v143, v136
	v_add_f32_e32 v160, v89, v149
	v_med3_f32 v136, v160, s6, v191
	v_mul_f32_e32 v136, 0xbfb8aa3b, v136
	v_pk_add_f32 v[142:143], v[142:143], 1.0 op_sel_hi:[1,0]
	v_exp_f32_e32 v160, v136
	v_mul_f32_e32 v136, v142, v159
	v_rcp_f32_e32 v136, v136
	v_and_b32_e32 v197, 0xffff0000, v137
	v_add_f32_e32 v160, 1.0, v160
	v_mul_f32_e32 v137, v159, v136
	v_mul_f32_e32 v159, 0x437f0000, v137
	v_mul_f32_e32 v137, v143, v160
	v_rcp_f32_e32 v137, v137
	v_rndne_f32_e32 v159, v159
	v_cvt_f16_f32_e32 v159, v159
	v_pk_mul_f32 v[142:143], v[142:143], v[136:137]
	v_mul_f32_e32 v136, v160, v137
	v_add_f32_e32 v137, v90, v150
	v_med3_f32 v137, v137, s6, v191
	v_mul_f32_e32 v137, 0xbfb8aa3b, v137
	v_exp_f32_e32 v137, v137
	v_pk_mul_f32 v[140:141], v[142:143], v[140:141]
	v_mul_f32_e32 v136, 0x437f0000, v136
	v_cvt_pk_f16_f32 v198, v140, v141
	v_rndne_f32_e32 v141, v136
	v_add_f32_e32 v136, v94, v146
	v_add_f32_e32 v142, 1.0, v137
	v_add_f32_e32 v137, v95, v147
	v_med3_f32 v136, v136, s6, v191
	v_med3_f32 v137, v137, s6, v191
	v_mul_f32_e32 v136, 0xbfb8aa3b, v136
	v_mul_f32_e32 v137, 0xbfb8aa3b, v137
	v_exp_f32_e32 v136, v136
	v_exp_f32_e32 v137, v137
	v_add_f32_e32 v140, v91, v151
	v_med3_f32 v140, v140, s6, v191
	v_mul_f32_e32 v140, 0xbfb8aa3b, v140
	v_pk_add_f32 v[136:137], v[136:137], 1.0 op_sel_hi:[1,0]
	v_exp_f32_e32 v143, v140
	v_mul_f32_e32 v140, v136, v142
	v_rcp_f32_e32 v140, v140
	v_cvt_f16_f32_e32 v160, v141
	v_add_f32_e32 v143, 1.0, v143
	v_mul_f32_e32 v141, v142, v140
	v_mul_f32_e32 v142, 0x437f0000, v141
	v_mul_f32_e32 v141, v137, v143
	v_rcp_f32_e32 v141, v141
	v_rndne_f32_e32 v142, v142
	v_cvt_f16_f32_e32 v142, v142
	v_mul_f32_e32 v143, v143, v141
	v_mul_f32_e32 v143, 0x437f0000, v143
	v_rndne_f32_e32 v143, v143
	v_cvt_f16_f32_e32 v143, v143
	v_pk_mul_f32 v[136:137], v[136:137], v[140:141]
	v_bfi_b32 v141, s98, v160, v198
	v_pk_mul_f32 v[136:137], v[136:137], v[196:197]
	v_pack_b32_f16 v140, v159, v198
	v_cvt_pk_f16_f32 v136, v136, v137
	v_bfi_b32 v143, s98, v143, v136
	v_pack_b32_f16 v142, v142, v136
	ds_write_b128 v158, v[140:143] offset:8192
	v_add_f32_e32 v140, v72, v148
	v_lshlrev_b32_e32 v136, 16, v138
	v_and_b32_e32 v137, 0xffff0000, v138
	v_add_f32_e32 v138, v76, v144
	v_med3_f32 v140, v140, s6, v191
	v_mul_f32_e32 v140, 0xbfb8aa3b, v140
	v_med3_f32 v138, v138, s6, v191
	v_exp_f32_e32 v141, v140
	v_mul_f32_e32 v138, 0xbfb8aa3b, v138
	v_exp_f32_e32 v140, v138
	v_add_f32_e32 v138, v77, v145
	v_med3_f32 v138, v138, s6, v191
	v_mul_f32_e32 v138, 0xbfb8aa3b, v138
	v_add_f32_e32 v159, 1.0, v141
	v_exp_f32_e32 v141, v138
	v_add_f32_e32 v142, v73, v149
	v_med3_f32 v138, v142, s6, v191
	v_mul_f32_e32 v138, 0xbfb8aa3b, v138
	v_pk_add_f32 v[140:141], v[140:141], 1.0 op_sel_hi:[1,0]
	v_exp_f32_e32 v160, v138
	v_mul_f32_e32 v138, v140, v159
	v_rcp_f32_e32 v138, v138
	v_lshlrev_b32_e32 v142, 16, v139
	v_and_b32_e32 v143, 0xffff0000, v139
	v_add_f32_e32 v160, 1.0, v160
	v_mul_f32_e32 v139, v159, v138
	v_mul_f32_e32 v159, 0x437f0000, v139
	v_mul_f32_e32 v139, v141, v160
	v_rcp_f32_e32 v139, v139
	v_rndne_f32_e32 v159, v159
	v_cvt_f16_f32_e32 v159, v159
	v_pk_mul_f32 v[140:141], v[140:141], v[138:139]
	v_add_f32_e32 v138, v75, v151
	v_pk_mul_f32 v[136:137], v[140:141], v[136:137]
	v_med3_f32 v138, v138, s6, v191
	v_cvt_pk_f16_f32 v140, v136, v137
	v_add_f32_e32 v137, v74, v150
	v_med3_f32 v137, v137, s6, v191
	v_mul_f32_e32 v137, 0xbfb8aa3b, v137
	v_exp_f32_e32 v137, v137
	v_mul_f32_e32 v136, v160, v139
	v_mul_f32_e32 v136, 0x437f0000, v136
	v_rndne_f32_e32 v139, v136
	v_add_f32_e32 v136, v78, v146
	v_add_f32_e32 v141, 1.0, v137
	v_add_f32_e32 v137, v79, v147
	v_med3_f32 v136, v136, s6, v191
	v_med3_f32 v137, v137, s6, v191
	v_mul_f32_e32 v136, 0xbfb8aa3b, v136
	v_mul_f32_e32 v137, 0xbfb8aa3b, v137
	v_exp_f32_e32 v136, v136
	v_exp_f32_e32 v137, v137
	v_mul_f32_e32 v138, 0xbfb8aa3b, v138
	v_exp_f32_e32 v160, v138
	v_pk_add_f32 v[136:137], v[136:137], 1.0 op_sel_hi:[1,0]
	v_cvt_f16_f32_e32 v196, v139
	v_mul_f32_e32 v138, v136, v141
	v_rcp_f32_e32 v138, v138
	v_add_f32_e32 v160, 1.0, v160
	v_mul_f32_e32 v139, v141, v138
	v_mul_f32_e32 v141, 0x437f0000, v139
	v_mul_f32_e32 v139, v137, v160
	v_rcp_f32_e32 v139, v139
	v_rndne_f32_e32 v141, v141
	v_cvt_f16_f32_e32 v141, v141
	v_mul_f32_e32 v160, v160, v139
	v_mul_f32_e32 v160, 0x437f0000, v160
	v_rndne_f32_e32 v160, v160
	v_cvt_f16_f32_e32 v160, v160
	v_pk_mul_f32 v[136:137], v[136:137], v[138:139]
	s_nop 0
	v_pk_mul_f32 v[136:137], v[136:137], v[142:143]
	s_nop 0
	v_cvt_pk_f16_f32 v136, v136, v137
	v_bfi_b32 v139, s98, v160, v136
	v_bfi_b32 v137, s98, v196, v140
	v_pack_b32_f16 v138, v141, v136
	v_pack_b32_f16 v136, v159, v140
	ds_write_b128 v158, v[136:139] offset:12288
	v_add_f32_e32 v138, v56, v148
	v_lshlrev_b32_e32 v136, 16, v132
	v_and_b32_e32 v137, 0xffff0000, v132
	v_add_f32_e32 v132, v60, v144
	v_med3_f32 v138, v138, s6, v191
	v_mul_f32_e32 v138, 0xbfb8aa3b, v138
	v_med3_f32 v132, v132, s6, v191
	v_exp_f32_e32 v139, v138
	v_mul_f32_e32 v132, 0xbfb8aa3b, v132
	v_exp_f32_e32 v138, v132
	v_add_f32_e32 v132, v61, v145
	v_med3_f32 v132, v132, s6, v191
	v_mul_f32_e32 v132, 0xbfb8aa3b, v132
	v_add_f32_e32 v142, 1.0, v139
	v_exp_f32_e32 v139, v132
	v_add_f32_e32 v140, v57, v149
	v_med3_f32 v132, v140, s6, v191
	v_mul_f32_e32 v132, 0xbfb8aa3b, v132
	v_pk_add_f32 v[138:139], v[138:139], 1.0 op_sel_hi:[1,0]
	v_exp_f32_e32 v143, v132
	v_mul_f32_e32 v132, v138, v142
	v_rcp_f32_e32 v132, v132
	v_lshlrev_b32_e32 v140, 16, v133
	v_and_b32_e32 v141, 0xffff0000, v133
	v_add_f32_e32 v143, 1.0, v143
	v_mul_f32_e32 v133, v142, v132
	v_mul_f32_e32 v142, 0x437f0000, v133
	v_mul_f32_e32 v133, v139, v143
	v_rcp_f32_e32 v133, v133
	v_rndne_f32_e32 v142, v142
	v_cvt_f16_f32_e32 v142, v142
	v_pk_mul_f32 v[138:139], v[138:139], v[132:133]
	v_mul_f32_e32 v132, v143, v133
	v_add_f32_e32 v133, v58, v150
	v_med3_f32 v133, v133, s6, v191
	v_mul_f32_e32 v133, 0xbfb8aa3b, v133
	v_exp_f32_e32 v133, v133
	v_pk_mul_f32 v[136:137], v[138:139], v[136:137]
	v_mul_f32_e32 v132, 0x437f0000, v132
	v_cvt_pk_f16_f32 v159, v136, v137
	v_rndne_f32_e32 v137, v132
	v_add_f32_e32 v132, v62, v146
	v_add_f32_e32 v138, 1.0, v133
	v_add_f32_e32 v133, v63, v147
	v_med3_f32 v132, v132, s6, v191
	v_med3_f32 v133, v133, s6, v191
	v_mul_f32_e32 v132, 0xbfb8aa3b, v132
	v_mul_f32_e32 v133, 0xbfb8aa3b, v133
	v_exp_f32_e32 v132, v132
	v_exp_f32_e32 v133, v133
	v_add_f32_e32 v136, v59, v151
	v_med3_f32 v136, v136, s6, v191
	v_mul_f32_e32 v136, 0xbfb8aa3b, v136
	v_pk_add_f32 v[132:133], v[132:133], 1.0 op_sel_hi:[1,0]
	v_exp_f32_e32 v139, v136
	v_mul_f32_e32 v136, v132, v138
	v_rcp_f32_e32 v136, v136
	v_cvt_f16_f32_e32 v143, v137
	v_add_f32_e32 v139, 1.0, v139
	v_mul_f32_e32 v137, v138, v136
	v_mul_f32_e32 v138, 0x437f0000, v137
	v_mul_f32_e32 v137, v133, v139
	v_rcp_f32_e32 v137, v137
	v_rndne_f32_e32 v138, v138
	v_cvt_f16_f32_e32 v138, v138
	v_mul_f32_e32 v139, v139, v137
	v_mul_f32_e32 v139, 0x437f0000, v139
	v_rndne_f32_e32 v139, v139
	v_cvt_f16_f32_e32 v139, v139
	v_pk_mul_f32 v[132:133], v[132:133], v[136:137]
	v_bfi_b32 v137, s98, v143, v159
	v_pk_mul_f32 v[132:133], v[132:133], v[140:141]
	v_pack_b32_f16 v136, v142, v159
	v_cvt_pk_f16_f32 v132, v132, v133
	v_bfi_b32 v139, s98, v139, v132
	v_pack_b32_f16 v138, v138, v132
	ds_write_b128 v158, v[136:139] offset:16384
	v_add_f32_e32 v136, v40, v148
	v_lshlrev_b32_e32 v132, 16, v134
	v_and_b32_e32 v133, 0xffff0000, v134
	v_add_f32_e32 v134, v44, v144
	v_med3_f32 v136, v136, s6, v191
	v_mul_f32_e32 v136, 0xbfb8aa3b, v136
	v_med3_f32 v134, v134, s6, v191
	v_exp_f32_e32 v137, v136
	v_mul_f32_e32 v134, 0xbfb8aa3b, v134
	v_exp_f32_e32 v136, v134
	v_add_f32_e32 v134, v45, v145
	v_med3_f32 v134, v134, s6, v191
	v_mul_f32_e32 v134, 0xbfb8aa3b, v134
	v_add_f32_e32 v140, 1.0, v137
	v_exp_f32_e32 v137, v134
	v_add_f32_e32 v138, v41, v149
	v_med3_f32 v134, v138, s6, v191
	v_mul_f32_e32 v134, 0xbfb8aa3b, v134
	v_pk_add_f32 v[136:137], v[136:137], 1.0 op_sel_hi:[1,0]
	v_exp_f32_e32 v141, v134
	v_mul_f32_e32 v134, v136, v140
	v_rcp_f32_e32 v134, v134
	v_lshlrev_b32_e32 v138, 16, v135
	v_and_b32_e32 v139, 0xffff0000, v135
	v_add_f32_e32 v141, 1.0, v141
	v_mul_f32_e32 v135, v140, v134
	v_mul_f32_e32 v140, 0x437f0000, v135
	v_mul_f32_e32 v135, v137, v141
	v_rcp_f32_e32 v135, v135
	v_rndne_f32_e32 v140, v140
	v_cvt_f16_f32_e32 v140, v140
	v_pk_mul_f32 v[136:137], v[136:137], v[134:135]
	v_add_f32_e32 v134, v43, v151
	v_pk_mul_f32 v[132:133], v[136:137], v[132:133]
	v_med3_f32 v134, v134, s6, v191
	v_cvt_pk_f16_f32 v136, v132, v133
	v_add_f32_e32 v133, v42, v150
	v_med3_f32 v133, v133, s6, v191
	v_mul_f32_e32 v133, 0xbfb8aa3b, v133
	v_exp_f32_e32 v133, v133
	v_mul_f32_e32 v132, v141, v135
	v_mul_f32_e32 v132, 0x437f0000, v132
	v_rndne_f32_e32 v135, v132
	v_add_f32_e32 v132, v46, v146
	v_add_f32_e32 v137, 1.0, v133
	v_add_f32_e32 v133, v47, v147
	v_med3_f32 v132, v132, s6, v191
	v_med3_f32 v133, v133, s6, v191
	v_mul_f32_e32 v132, 0xbfb8aa3b, v132
	v_mul_f32_e32 v133, 0xbfb8aa3b, v133
	v_exp_f32_e32 v132, v132
	v_exp_f32_e32 v133, v133
	v_mul_f32_e32 v134, 0xbfb8aa3b, v134
	v_exp_f32_e32 v141, v134
	v_pk_add_f32 v[132:133], v[132:133], 1.0 op_sel_hi:[1,0]
	v_cvt_f16_f32_e32 v142, v135
	v_mul_f32_e32 v134, v132, v137
	v_rcp_f32_e32 v134, v134
	v_add_f32_e32 v141, 1.0, v141
	v_mul_f32_e32 v135, v137, v134
	v_mul_f32_e32 v137, 0x437f0000, v135
	v_mul_f32_e32 v135, v133, v141
	v_rcp_f32_e32 v135, v135
	v_rndne_f32_e32 v137, v137
	v_cvt_f16_f32_e32 v137, v137
	v_mul_f32_e32 v141, v141, v135
	v_mul_f32_e32 v141, 0x437f0000, v141
	v_rndne_f32_e32 v141, v141
	v_cvt_f16_f32_e32 v141, v141
	v_pk_mul_f32 v[132:133], v[132:133], v[134:135]
	s_nop 0
	v_pk_mul_f32 v[132:133], v[132:133], v[138:139]
	s_nop 0
	v_cvt_pk_f16_f32 v132, v132, v133
	v_bfi_b32 v135, s98, v141, v132
	v_bfi_b32 v133, s98, v142, v136
	v_pack_b32_f16 v134, v137, v132
	v_pack_b32_f16 v132, v140, v136
	ds_write_b128 v158, v[132:135] offset:20480
	v_add_f32_e32 v134, v24, v148
	v_lshlrev_b32_e32 v132, 16, v128
	v_and_b32_e32 v133, 0xffff0000, v128
	v_add_f32_e32 v128, v28, v144
	v_med3_f32 v134, v134, s6, v191
	v_mul_f32_e32 v134, 0xbfb8aa3b, v134
	v_med3_f32 v128, v128, s6, v191
	v_exp_f32_e32 v135, v134
	v_mul_f32_e32 v128, 0xbfb8aa3b, v128
	v_exp_f32_e32 v134, v128
	v_add_f32_e32 v128, v29, v145
	v_med3_f32 v128, v128, s6, v191
	v_mul_f32_e32 v128, 0xbfb8aa3b, v128
	v_add_f32_e32 v138, 1.0, v135
	v_exp_f32_e32 v135, v128
	v_add_f32_e32 v136, v25, v149
	v_med3_f32 v128, v136, s6, v191
	v_mul_f32_e32 v128, 0xbfb8aa3b, v128
	v_pk_add_f32 v[134:135], v[134:135], 1.0 op_sel_hi:[1,0]
	v_exp_f32_e32 v139, v128
	v_mul_f32_e32 v128, v134, v138
	v_rcp_f32_e32 v128, v128
	v_lshlrev_b32_e32 v136, 16, v129
	v_and_b32_e32 v137, 0xffff0000, v129
	v_add_f32_e32 v139, 1.0, v139
	v_mul_f32_e32 v129, v138, v128
	v_mul_f32_e32 v138, 0x437f0000, v129
	v_mul_f32_e32 v129, v135, v139
	v_rcp_f32_e32 v129, v129
	v_rndne_f32_e32 v138, v138
	v_cvt_f16_f32_e32 v138, v138
	v_pk_mul_f32 v[134:135], v[134:135], v[128:129]
	v_mul_f32_e32 v128, v139, v129
	v_add_f32_e32 v129, v26, v150
	v_med3_f32 v129, v129, s6, v191
	v_mul_f32_e32 v129, 0xbfb8aa3b, v129
	v_exp_f32_e32 v129, v129
	v_pk_mul_f32 v[132:133], v[134:135], v[132:133]
	v_mul_f32_e32 v128, 0x437f0000, v128
	v_cvt_pk_f16_f32 v140, v132, v133
	v_rndne_f32_e32 v133, v128
	v_add_f32_e32 v128, v30, v146
	v_add_f32_e32 v134, 1.0, v129
	v_add_f32_e32 v129, v31, v147
	v_med3_f32 v128, v128, s6, v191
	v_med3_f32 v129, v129, s6, v191
	v_mul_f32_e32 v128, 0xbfb8aa3b, v128
	v_mul_f32_e32 v129, 0xbfb8aa3b, v129
	v_exp_f32_e32 v128, v128
	v_exp_f32_e32 v129, v129
	v_add_f32_e32 v132, v27, v151
	v_med3_f32 v132, v132, s6, v191
	v_mul_f32_e32 v132, 0xbfb8aa3b, v132
	v_pk_add_f32 v[128:129], v[128:129], 1.0 op_sel_hi:[1,0]
	v_exp_f32_e32 v135, v132
	v_mul_f32_e32 v132, v128, v134
	v_rcp_f32_e32 v132, v132
	v_cvt_f16_f32_e32 v139, v133
	v_add_f32_e32 v135, 1.0, v135
	v_mul_f32_e32 v133, v134, v132
	v_mul_f32_e32 v134, 0x437f0000, v133
	v_mul_f32_e32 v133, v129, v135
	v_rcp_f32_e32 v133, v133
	v_rndne_f32_e32 v134, v134
	v_cvt_f16_f32_e32 v134, v134
	v_mul_f32_e32 v135, v135, v133
	v_mul_f32_e32 v135, 0x437f0000, v135
	v_rndne_f32_e32 v135, v135
	v_cvt_f16_f32_e32 v135, v135
	v_pk_mul_f32 v[128:129], v[128:129], v[132:133]
	v_bfi_b32 v133, s98, v139, v140
	v_pk_mul_f32 v[128:129], v[128:129], v[136:137]
	v_pack_b32_f16 v132, v138, v140
	v_cvt_pk_f16_f32 v128, v128, v129
	v_bfi_b32 v135, s98, v135, v128
	v_pack_b32_f16 v134, v134, v128
	ds_write_b128 v158, v[132:135] offset:24576
	v_add_f32_e32 v132, v8, v148
	v_lshlrev_b32_e32 v128, 16, v130
	v_and_b32_e32 v129, 0xffff0000, v130
	v_add_f32_e32 v130, v12, v144
	v_med3_f32 v132, v132, s6, v191
	v_mul_f32_e32 v132, 0xbfb8aa3b, v132
	v_med3_f32 v130, v130, s6, v191
	v_exp_f32_e32 v133, v132
	v_mul_f32_e32 v130, 0xbfb8aa3b, v130
	v_exp_f32_e32 v132, v130
	v_add_f32_e32 v130, v13, v145
	v_med3_f32 v130, v130, s6, v191
	v_mul_f32_e32 v130, 0xbfb8aa3b, v130
	v_add_f32_e32 v136, 1.0, v133
	v_exp_f32_e32 v133, v130
	v_add_f32_e32 v134, v9, v149
	v_med3_f32 v130, v134, s6, v191
	v_mul_f32_e32 v130, 0xbfb8aa3b, v130
	v_pk_add_f32 v[132:133], v[132:133], 1.0 op_sel_hi:[1,0]
	v_exp_f32_e32 v137, v130
	v_mul_f32_e32 v130, v132, v136
	v_rcp_f32_e32 v130, v130
	v_lshlrev_b32_e32 v134, 16, v131
	v_and_b32_e32 v135, 0xffff0000, v131
	v_add_f32_e32 v137, 1.0, v137
	v_mul_f32_e32 v131, v136, v130
	v_mul_f32_e32 v136, 0x437f0000, v131
	v_mul_f32_e32 v131, v133, v137
	v_rcp_f32_e32 v131, v131
	v_rndne_f32_e32 v136, v136
	v_cvt_f16_f32_e32 v136, v136
	v_pk_mul_f32 v[132:133], v[132:133], v[130:131]
	v_add_f32_e32 v130, v11, v151
	v_pk_mul_f32 v[128:129], v[132:133], v[128:129]
	v_med3_f32 v130, v130, s6, v191
	v_cvt_pk_f16_f32 v132, v128, v129
	v_add_f32_e32 v129, v10, v150
	v_med3_f32 v129, v129, s6, v191
	v_mul_f32_e32 v129, 0xbfb8aa3b, v129
	v_exp_f32_e32 v129, v129
	v_mul_f32_e32 v128, v137, v131
	v_mul_f32_e32 v128, 0x437f0000, v128
	v_rndne_f32_e32 v131, v128
	v_add_f32_e32 v128, v14, v146
	v_add_f32_e32 v133, 1.0, v129
	v_add_f32_e32 v129, v15, v147
	v_med3_f32 v128, v128, s6, v191
	v_med3_f32 v129, v129, s6, v191
	v_mul_f32_e32 v128, 0xbfb8aa3b, v128
	v_mul_f32_e32 v129, 0xbfb8aa3b, v129
	v_exp_f32_e32 v128, v128
	v_exp_f32_e32 v129, v129
	v_mul_f32_e32 v130, 0xbfb8aa3b, v130
	v_exp_f32_e32 v137, v130
	v_pk_add_f32 v[128:129], v[128:129], 1.0 op_sel_hi:[1,0]
	v_cvt_f16_f32_e32 v138, v131
	v_mul_f32_e32 v130, v128, v133
	v_rcp_f32_e32 v130, v130
	v_add_f32_e32 v137, 1.0, v137
	v_mul_f32_e32 v131, v133, v130
	v_mul_f32_e32 v133, 0x437f0000, v131
	v_mul_f32_e32 v131, v129, v137
	v_rcp_f32_e32 v131, v131
	v_rndne_f32_e32 v133, v133
	v_cvt_f16_f32_e32 v133, v133
	v_mul_f32_e32 v137, v137, v131
	v_mul_f32_e32 v137, 0x437f0000, v137
	v_rndne_f32_e32 v137, v137
	v_cvt_f16_f32_e32 v137, v137
	v_pk_mul_f32 v[128:129], v[128:129], v[130:131]
	s_nop 0
	v_pk_mul_f32 v[128:129], v[128:129], v[134:135]
	s_nop 0
	v_cvt_pk_f16_f32 v128, v128, v129
	v_bfi_b32 v131, s98, v137, v128
	v_bfi_b32 v129, s98, v138, v132
	v_pack_b32_f16 v130, v133, v128
	v_pack_b32_f16 v128, v136, v132
	ds_write_b128 v158, v[128:131] offset:28672
	v_cndmask_b32_e64 v128, v200, v156, s[4:5]
	v_and_b32_e32 v140, 7, v128
	v_ashrrev_i32_e32 v136, 3, v128
	v_lshlrev_b32_e32 v133, 1, v140
	v_lshl_add_u32 v132, v136, 8, v192
	v_bitop3_b32 v128, v133, v136, 15 bitop3:0x78
	v_lshl_or_b32 v128, v128, 4, v132
	s_waitcnt lgkmcnt(0)
	s_barrier
	ds_read_b128 v[128:131], v128
	v_and_b32_e32 v134, 15, v136
	v_bitop3_b32 v133, v133, v134, 1 bitop3:0x36
	v_lshl_or_b32 v132, v133, 4, v132
	ds_read_b128 v[132:135], v132
	s_waitcnt lgkmcnt(0)
	v_cvt_f32_f16_e32 v137, v128
	v_cvt_f32_f16_e32 v138, v129
	v_cvt_f32_f16_e32 v139, v130
	v_cvt_f32_f16_e32 v141, v131
	v_cvt_u32_f32_e32 v137, v137
	v_cvt_u32_f32_e32 v138, v138
	v_cvt_u32_f32_sdwa v139, v139 dst_sel:WORD_1 dst_unused:UNUSED_PAD src0_sel:DWORD
	v_cvt_u32_f32_sdwa v141, v141 dst_sel:BYTE_3 dst_unused:UNUSED_PAD src0_sel:DWORD
	v_and_b32_e32 v131, 0xffff0000, v131
	v_and_b32_e32 v142, 0xffff0000, v129
	v_lshl_or_b32 v129, v138, 8, v137
	v_or3_b32 v138, v129, v139, v141
	v_or_b32_sdwa v129, v131, v130 dst_sel:DWORD dst_unused:UNUSED_PAD src0_sel:DWORD src1_sel:WORD_1
	v_cvt_f32_f16_e32 v130, v132
	v_cvt_f32_f16_e32 v131, v133
	v_cvt_f32_f16_e32 v137, v134
	v_cvt_f32_f16_e32 v139, v135
	v_cvt_u32_f32_e32 v130, v130
	v_cvt_u32_f32_e32 v131, v131
	v_cvt_u32_f32_sdwa v137, v137 dst_sel:WORD_1 dst_unused:UNUSED_PAD src0_sel:DWORD
	v_cvt_u32_f32_sdwa v139, v139 dst_sel:BYTE_3 dst_unused:UNUSED_PAD src0_sel:DWORD
	v_and_b32_e32 v133, 0xffff0000, v133
	v_lshl_or_b32 v130, v131, 8, v130
	v_and_b32_e32 v135, 0xffff0000, v135
	v_or3_b32 v139, v130, v137, v139
	v_ashrrev_i32_e32 v137, 31, v136
	v_or_b32_sdwa v130, v133, v132 dst_sel:DWORD dst_unused:UNUSED_PAD src0_sel:DWORD src1_sel:WORD_1
	v_lshlrev_b64 v[132:133], 10, v[136:137]
	v_or_b32_sdwa v131, v135, v134 dst_sel:DWORD dst_unused:UNUSED_PAD src0_sel:DWORD src1_sel:WORD_1
	v_lshl_add_u64 v[132:133], s[12:13], 0, v[132:133]
	v_lshlrev_b32_e32 v134, 3, v140
	v_mov_b32_e32 v135, v164
	v_lshl_add_u64 v[132:133], v[132:133], 0, v[134:135]
	global_store_dwordx2 v[132:133], v[138:139], off
	v_lshlrev_b32_e32 v132, 4, v140
	v_or_b32_sdwa v128, v142, v128 dst_sel:DWORD dst_unused:UNUSED_PAD src0_sel:DWORD src1_sel:WORD_1
	v_lshl_or_b32 v132, v136, 11, v132
	buffer_store_dwordx4 v[128:131], v132, s[8:11], 0 offen sc1
	s_nop 1
	v_add_u32_e32 v128, 0x200, v156
	v_cndmask_b32_e64 v128, v128, v200, s[4:5]
	v_and_b32_e32 v140, 7, v128
	v_ashrrev_i32_e32 v136, 3, v128
	v_lshlrev_b32_e32 v132, 1, v140
	v_bitop3_b32 v128, v132, v136, 15 bitop3:0x78
	v_lshl_add_u32 v197, v136, 8, v192
	v_lshlrev_b32_e32 v199, 4, v128
	v_or_b32_e32 v128, v197, v199
	ds_read_b128 v[128:131], v128
	v_and_b32_e32 v133, 15, v136
	v_bitop3_b32 v132, v132, v133, 1 bitop3:0x36
	v_lshlrev_b32_e32 v198, 4, v132
	v_or_b32_e32 v132, v197, v198
	ds_read_b128 v[132:135], v132
	s_waitcnt lgkmcnt(1)
	v_cvt_f32_f16_e32 v137, v128
	v_cvt_f32_f16_e32 v138, v129
	v_cvt_f32_f16_e32 v139, v130
	v_cvt_f32_f16_e32 v141, v131
	v_cvt_u32_f32_e32 v137, v137
	v_cvt_u32_f32_e32 v138, v138
	v_cvt_u32_f32_sdwa v139, v139 dst_sel:WORD_1 dst_unused:UNUSED_PAD src0_sel:DWORD
	v_cvt_u32_f32_sdwa v141, v141 dst_sel:BYTE_3 dst_unused:UNUSED_PAD src0_sel:DWORD
	v_and_b32_e32 v131, 0xffff0000, v131
	v_and_b32_e32 v142, 0xffff0000, v129
	v_lshl_or_b32 v129, v138, 8, v137
	v_or3_b32 v138, v129, v139, v141
	v_or_b32_sdwa v129, v131, v130 dst_sel:DWORD dst_unused:UNUSED_PAD src0_sel:DWORD src1_sel:WORD_1
	s_waitcnt lgkmcnt(0)
	v_cvt_f32_f16_e32 v130, v132
	v_cvt_f32_f16_e32 v131, v133
	v_cvt_f32_f16_e32 v137, v134
	v_cvt_f32_f16_e32 v139, v135
	v_cvt_u32_f32_e32 v130, v130
	v_cvt_u32_f32_e32 v131, v131
	v_cvt_u32_f32_sdwa v137, v137 dst_sel:WORD_1 dst_unused:UNUSED_PAD src0_sel:DWORD
	v_cvt_u32_f32_sdwa v139, v139 dst_sel:BYTE_3 dst_unused:UNUSED_PAD src0_sel:DWORD
	v_and_b32_e32 v133, 0xffff0000, v133
	v_lshl_or_b32 v130, v131, 8, v130
	v_and_b32_e32 v135, 0xffff0000, v135
	v_or3_b32 v139, v130, v137, v139
	v_ashrrev_i32_e32 v137, 31, v136
	v_or_b32_sdwa v130, v133, v132 dst_sel:DWORD dst_unused:UNUSED_PAD src0_sel:DWORD src1_sel:WORD_1
	v_lshlrev_b64 v[132:133], 10, v[136:137]
	v_or_b32_sdwa v131, v135, v134 dst_sel:DWORD dst_unused:UNUSED_PAD src0_sel:DWORD src1_sel:WORD_1
	v_lshl_add_u64 v[132:133], s[12:13], 0, v[132:133]
	v_lshlrev_b32_e32 v134, 3, v140
	v_mov_b32_e32 v135, v164
	v_lshl_add_u64 v[150:151], v[132:133], 0, v[134:135]
	v_lshlrev_b32_e32 v132, 4, v140
	v_or_b32_sdwa v128, v142, v128 dst_sel:DWORD dst_unused:UNUSED_PAD src0_sel:DWORD src1_sel:WORD_1
	v_lshl_or_b32 v196, v136, 11, v132
	global_store_dwordx2 v[150:151], v[138:139], off
	buffer_store_dwordx4 v[128:131], v196, s[8:11], 0 offen sc1
	v_add_u32_e32 v132, 0x600, v156
	v_ashrrev_i32_e32 v142, 3, v132
	v_add_u32_e32 v128, 0x300, v156
	v_and_b32_e32 v129, 7, v157
	v_add_u32_e32 v130, 0x400, v156
	v_add_u32_e32 v131, 0x500, v156
	v_ashrrev_i32_e32 v148, 3, v128
	v_lshlrev_b32_e32 v160, 1, v129
	v_lshlrev_b32_e32 v140, 3, v129
	v_lshlrev_b32_e32 v159, 4, v129
	v_ashrrev_i32_e32 v146, 3, v130
	v_ashrrev_i32_e32 v144, 3, v131
	s_and_saveexec_b64 s[4:5], vcc
	s_xor_b64 s[4:5], exec, s[4:5]
	s_cbranch_execz .LBB0_459
	v_lshl_add_u32 v129, v148, 8, v192
	v_bitop3_b32 v128, v148, v160, 15 bitop3:0x6c
	v_lshl_or_b32 v130, v128, 4, v129
	v_or_b32_e32 v128, 1, v160
	v_bitop3_b32 v131, v148, v128, 15 bitop3:0x6c
	v_lshl_or_b32 v129, v131, 4, v129
	ds_read_b128 v[130:133], v130
	v_ashrrev_i32_e32 v149, 31, v148
	v_mov_b32_e32 v141, v164
	v_ashrrev_i32_e32 v147, 31, v146
	v_ashrrev_i32_e32 v145, 31, v144
	s_waitcnt lgkmcnt(0)
	v_and_b32_e32 v135, 0xffff0000, v131
	v_cvt_f32_f16_e32 v136, v130
	v_cvt_f32_f16_e32 v131, v131
	v_and_b32_e32 v134, 0xffff0000, v133
	v_cvt_f32_f16_e32 v137, v132
	v_cvt_f32_f16_e32 v133, v133
	v_cvt_u32_f32_e32 v136, v136
	v_cvt_u32_f32_e32 v131, v131
	v_cvt_u32_f32_sdwa v137, v137 dst_sel:WORD_1 dst_unused:UNUSED_PAD src0_sel:DWORD
	v_cvt_u32_f32_sdwa v133, v133 dst_sel:BYTE_3 dst_unused:UNUSED_PAD src0_sel:DWORD
	v_or_b32_sdwa v130, v135, v130 dst_sel:DWORD dst_unused:UNUSED_PAD src0_sel:DWORD src1_sel:WORD_1
	v_lshl_or_b32 v131, v131, 8, v136
	v_ashrrev_i32_e32 v143, 31, v142
	v_or3_b32 v136, v131, v137, v133
	v_or_b32_sdwa v131, v134, v132 dst_sel:DWORD dst_unused:UNUSED_PAD src0_sel:DWORD src1_sel:WORD_1
	ds_read_b128 v[132:135], v129
	s_waitcnt lgkmcnt(0)
	v_and_b32_e32 v138, 0xffff0000, v133
	v_cvt_f32_f16_e32 v137, v132
	v_cvt_f32_f16_e32 v133, v133
	v_and_b32_e32 v129, 0xffff0000, v135
	v_cvt_f32_f16_e32 v139, v134
	v_cvt_f32_f16_e32 v135, v135
	v_cvt_u32_f32_e32 v137, v137
	v_cvt_u32_f32_e32 v133, v133
	v_cvt_u32_f32_sdwa v139, v139 dst_sel:WORD_1 dst_unused:UNUSED_PAD src0_sel:DWORD
	v_cvt_u32_f32_sdwa v135, v135 dst_sel:BYTE_3 dst_unused:UNUSED_PAD src0_sel:DWORD
	v_or_b32_sdwa v132, v138, v132 dst_sel:DWORD dst_unused:UNUSED_PAD src0_sel:DWORD src1_sel:WORD_1
	v_lshl_or_b32 v133, v133, 8, v137
	v_or3_b32 v137, v133, v139, v135
	v_or_b32_sdwa v133, v129, v134 dst_sel:DWORD dst_unused:UNUSED_PAD src0_sel:DWORD src1_sel:WORD_1
	v_lshlrev_b64 v[134:135], 10, v[148:149]
	v_lshl_add_u64 v[134:135], s[12:13], 0, v[134:135]
	v_lshl_add_u64 v[134:135], v[134:135], 0, v[140:141]
	v_lshl_or_b32 v129, v148, 11, v159
	global_store_dwordx2 v[134:135], v[136:137], off
	buffer_store_dwordx4 v[130:133], v129, s[8:11], 0 offen sc1
	v_lshl_add_u32 v129, v146, 8, v192
	s_nop 0
	v_bitop3_b32 v130, v146, v160, 15 bitop3:0x6c
	v_lshl_or_b32 v130, v130, 4, v129
	v_bitop3_b32 v131, v146, v128, 15 bitop3:0x6c
	v_lshl_or_b32 v129, v131, 4, v129
	ds_read_b128 v[130:133], v130
	s_waitcnt lgkmcnt(0)
	v_and_b32_e32 v135, 0xffff0000, v131
	v_cvt_f32_f16_e32 v136, v130
	v_cvt_f32_f16_e32 v131, v131
	v_and_b32_e32 v134, 0xffff0000, v133
	v_cvt_f32_f16_e32 v137, v132
	v_cvt_f32_f16_e32 v133, v133
	v_cvt_u32_f32_e32 v136, v136
	v_cvt_u32_f32_e32 v131, v131
	v_cvt_u32_f32_sdwa v137, v137 dst_sel:WORD_1 dst_unused:UNUSED_PAD src0_sel:DWORD
	v_cvt_u32_f32_sdwa v133, v133 dst_sel:BYTE_3 dst_unused:UNUSED_PAD src0_sel:DWORD
	v_or_b32_sdwa v130, v135, v130 dst_sel:DWORD dst_unused:UNUSED_PAD src0_sel:DWORD src1_sel:WORD_1
	v_lshl_or_b32 v131, v131, 8, v136
	v_or3_b32 v136, v131, v137, v133
	v_or_b32_sdwa v131, v134, v132 dst_sel:DWORD dst_unused:UNUSED_PAD src0_sel:DWORD src1_sel:WORD_1
	ds_read_b128 v[132:135], v129
	s_waitcnt lgkmcnt(0)
	v_and_b32_e32 v138, 0xffff0000, v133
	v_cvt_f32_f16_e32 v137, v132
	v_cvt_f32_f16_e32 v133, v133
	v_and_b32_e32 v129, 0xffff0000, v135
	v_cvt_f32_f16_e32 v139, v134
	v_cvt_f32_f16_e32 v135, v135
	v_cvt_u32_f32_e32 v137, v137
	v_cvt_u32_f32_e32 v133, v133
	v_cvt_u32_f32_sdwa v139, v139 dst_sel:WORD_1 dst_unused:UNUSED_PAD src0_sel:DWORD
	v_cvt_u32_f32_sdwa v135, v135 dst_sel:BYTE_3 dst_unused:UNUSED_PAD src0_sel:DWORD
	v_or_b32_sdwa v132, v138, v132 dst_sel:DWORD dst_unused:UNUSED_PAD src0_sel:DWORD src1_sel:WORD_1
	v_lshl_or_b32 v133, v133, 8, v137
	v_or3_b32 v137, v133, v139, v135
	v_or_b32_sdwa v133, v129, v134 dst_sel:DWORD dst_unused:UNUSED_PAD src0_sel:DWORD src1_sel:WORD_1
	v_lshlrev_b64 v[134:135], 10, v[146:147]
	v_lshl_add_u64 v[134:135], s[12:13], 0, v[134:135]
	v_lshl_add_u64 v[134:135], v[134:135], 0, v[140:141]
	v_lshl_or_b32 v129, v146, 11, v159
	global_store_dwordx2 v[134:135], v[136:137], off
	buffer_store_dwordx4 v[130:133], v129, s[8:11], 0 offen sc1
	v_lshl_add_u32 v129, v144, 8, v192
	s_nop 0
	v_bitop3_b32 v130, v144, v160, 15 bitop3:0x6c
	v_lshl_or_b32 v130, v130, 4, v129
	v_bitop3_b32 v131, v144, v128, 15 bitop3:0x6c
	v_lshl_or_b32 v129, v131, 4, v129
	ds_read_b128 v[130:133], v130
	v_bitop3_b32 v128, v142, v128, 15 bitop3:0x6c
	s_waitcnt lgkmcnt(0)
	v_and_b32_e32 v135, 0xffff0000, v131
	v_cvt_f32_f16_e32 v136, v130
	v_cvt_f32_f16_e32 v131, v131
	v_and_b32_e32 v134, 0xffff0000, v133
	v_cvt_f32_f16_e32 v137, v132
	v_cvt_f32_f16_e32 v133, v133
	v_cvt_u32_f32_e32 v136, v136
	v_cvt_u32_f32_e32 v131, v131
	v_cvt_u32_f32_sdwa v137, v137 dst_sel:WORD_1 dst_unused:UNUSED_PAD src0_sel:DWORD
	v_cvt_u32_f32_sdwa v133, v133 dst_sel:BYTE_3 dst_unused:UNUSED_PAD src0_sel:DWORD
	v_or_b32_sdwa v130, v135, v130 dst_sel:DWORD dst_unused:UNUSED_PAD src0_sel:DWORD src1_sel:WORD_1
	v_lshl_or_b32 v131, v131, 8, v136
	v_or3_b32 v136, v131, v137, v133
	v_or_b32_sdwa v131, v134, v132 dst_sel:DWORD dst_unused:UNUSED_PAD src0_sel:DWORD src1_sel:WORD_1
	ds_read_b128 v[132:135], v129
	s_waitcnt lgkmcnt(0)
	v_and_b32_e32 v138, 0xffff0000, v133
	v_cvt_f32_f16_e32 v137, v132
	v_cvt_f32_f16_e32 v133, v133
	v_and_b32_e32 v129, 0xffff0000, v135
	v_cvt_f32_f16_e32 v139, v134
	v_cvt_f32_f16_e32 v135, v135
	v_cvt_u32_f32_e32 v137, v137
	v_cvt_u32_f32_e32 v133, v133
	v_cvt_u32_f32_sdwa v139, v139 dst_sel:WORD_1 dst_unused:UNUSED_PAD src0_sel:DWORD
	v_cvt_u32_f32_sdwa v135, v135 dst_sel:BYTE_3 dst_unused:UNUSED_PAD src0_sel:DWORD
	v_or_b32_sdwa v132, v138, v132 dst_sel:DWORD dst_unused:UNUSED_PAD src0_sel:DWORD src1_sel:WORD_1
	v_lshl_or_b32 v133, v133, 8, v137
	v_or3_b32 v137, v133, v139, v135
	v_or_b32_sdwa v133, v129, v134 dst_sel:DWORD dst_unused:UNUSED_PAD src0_sel:DWORD src1_sel:WORD_1
	v_lshlrev_b64 v[134:135], 10, v[144:145]
	v_lshl_add_u64 v[134:135], s[12:13], 0, v[134:135]
	v_lshl_add_u64 v[134:135], v[134:135], 0, v[140:141]
	v_lshl_or_b32 v129, v144, 11, v159
	global_store_dwordx2 v[134:135], v[136:137], off
	buffer_store_dwordx4 v[130:133], v129, s[8:11], 0 offen sc1
	v_lshl_add_u32 v129, v142, 8, v192
	s_nop 0
	v_bitop3_b32 v130, v142, v160, 15 bitop3:0x6c
	v_lshl_or_b32 v130, v130, 4, v129
	v_lshl_or_b32 v132, v128, 4, v129
	ds_read_b128 v[128:131], v130
	s_waitcnt lgkmcnt(0)
	v_and_b32_e32 v135, 0xffff0000, v129
	v_cvt_f32_f16_e32 v134, v128
	v_cvt_f32_f16_e32 v129, v129
	v_and_b32_e32 v133, 0xffff0000, v131
	v_cvt_f32_f16_e32 v136, v130
	v_cvt_f32_f16_e32 v131, v131
	v_cvt_u32_f32_e32 v134, v134
	v_cvt_u32_f32_e32 v129, v129
	v_cvt_u32_f32_sdwa v136, v136 dst_sel:WORD_1 dst_unused:UNUSED_PAD src0_sel:DWORD
	v_cvt_u32_f32_sdwa v131, v131 dst_sel:BYTE_3 dst_unused:UNUSED_PAD src0_sel:DWORD
	v_or_b32_sdwa v128, v135, v128 dst_sel:DWORD dst_unused:UNUSED_PAD src0_sel:DWORD src1_sel:WORD_1
	v_lshl_or_b32 v129, v129, 8, v134
	v_or3_b32 v134, v129, v136, v131
	v_or_b32_sdwa v129, v133, v130 dst_sel:DWORD dst_unused:UNUSED_PAD src0_sel:DWORD src1_sel:WORD_1
	ds_read_b128 v[130:133], v132
	s_waitcnt lgkmcnt(0)
	v_and_b32_e32 v137, 0xffff0000, v131
	v_cvt_f32_f16_e32 v135, v130
	v_cvt_f32_f16_e32 v131, v131
	v_and_b32_e32 v136, 0xffff0000, v133
	v_cvt_f32_f16_e32 v138, v132
	v_cvt_f32_f16_e32 v133, v133
	v_cvt_u32_f32_e32 v135, v135
	v_cvt_u32_f32_e32 v131, v131
	v_cvt_u32_f32_sdwa v138, v138 dst_sel:WORD_1 dst_unused:UNUSED_PAD src0_sel:DWORD
	v_cvt_u32_f32_sdwa v133, v133 dst_sel:BYTE_3 dst_unused:UNUSED_PAD src0_sel:DWORD
	v_or_b32_sdwa v130, v137, v130 dst_sel:DWORD dst_unused:UNUSED_PAD src0_sel:DWORD src1_sel:WORD_1
	v_lshl_or_b32 v131, v131, 8, v135
	v_or3_b32 v135, v131, v138, v133
	v_or_b32_sdwa v131, v136, v132 dst_sel:DWORD dst_unused:UNUSED_PAD src0_sel:DWORD src1_sel:WORD_1
	v_lshlrev_b64 v[132:133], 10, v[142:143]
	v_lshl_add_u64 v[132:133], s[12:13], 0, v[132:133]
	v_lshl_add_u64 v[132:133], v[132:133], 0, v[140:141]
	global_store_dwordx2 v[132:133], v[134:135], off
	v_lshl_or_b32 v132, v142, 11, v159
	buffer_store_dwordx4 v[128:131], v132, s[8:11], 0 offen sc1

.LBB0_463:
	s_or_b64 exec, exec, s[16:17]
	s_waitcnt lgkmcnt(0)
	s_barrier
	global_load_dwordx4 v[132:135], v[152:153], off offset:256
	global_load_dwordx4 v[128:131], v[154:155], off offset:256
	v_lshlrev_b32_e32 v152, 16, v180
	v_and_b32_e32 v153, 0xffff0000, v180
	v_lshlrev_b32_e32 v154, 16, v181
	v_and_b32_e32 v155, 0xffff0000, v181
	s_waitcnt vmcnt(1)
	v_add_f32_e32 v147, v116, v132
	v_med3_f32 v147, v147, s6, v191
	s_waitcnt vmcnt(0)
	v_add_f32_e32 v149, v112, v128
	v_med3_f32 v149, v149, s6, v191
	v_mul_f32_e32 v147, 0xbfb8aa3b, v147
	v_exp_f32_e32 v156, v147
	v_mul_f32_e32 v147, 0xbfb8aa3b, v149
	v_add_f32_e32 v149, v117, v133
	v_med3_f32 v149, v149, s6, v191
	v_add_f32_e32 v157, v113, v129
	v_med3_f32 v180, v157, s6, v191
	v_mul_f32_e32 v149, 0xbfb8aa3b, v149
	v_exp_f32_e32 v157, v149
	v_mul_f32_e32 v149, 0xbfb8aa3b, v180
	v_exp_f32_e32 v147, v147
	v_exp_f32_e32 v149, v149
	v_pk_add_f32 v[156:157], v[156:157], 1.0 op_sel_hi:[1,0]
	v_add_f32_e32 v147, 1.0, v147
	v_add_f32_e32 v149, 1.0, v149
	v_mul_f32_e32 v180, v156, v147
	v_mul_f32_e32 v181, v157, v149
	v_rcp_f32_e32 v180, v180
	v_rcp_f32_e32 v181, v181
	v_mul_f32_e32 v147, v147, v180
	v_pk_mul_f32 v[156:157], v[156:157], v[180:181]
	v_mul_f32_e32 v149, v149, v181
	v_pk_mul_f32 v[152:153], v[156:157], v[152:153]
	v_add_f32_e32 v156, v115, v131
	v_cvt_pk_f16_f32 v180, v152, v153
	v_add_f32_e32 v153, v114, v130
	v_med3_f32 v153, v153, s6, v191
	v_mul_f32_e32 v153, 0xbfb8aa3b, v153
	v_exp_f32_e32 v153, v153
	v_add_f32_e32 v152, v118, v134
	v_med3_f32 v152, v152, s6, v191
	v_mul_f32_e32 v152, 0xbfb8aa3b, v152
	v_add_f32_e32 v157, 1.0, v153
	v_add_f32_e32 v153, v119, v135
	v_med3_f32 v153, v153, s6, v191
	v_med3_f32 v156, v156, s6, v191
	v_mul_f32_e32 v153, 0xbfb8aa3b, v153
	v_exp_f32_e32 v152, v152
	v_exp_f32_e32 v153, v153
	v_mul_f32_e32 v156, 0xbfb8aa3b, v156
	v_exp_f32_e32 v156, v156
	v_mul_f32_e32 v147, 0x437f0000, v147
	v_pk_add_f32 v[152:153], v[152:153], 1.0 op_sel_hi:[1,0]
	v_rndne_f32_e32 v147, v147
	v_add_f32_e32 v181, 1.0, v156
	v_mul_f32_e32 v156, v152, v157
	v_rcp_f32_e32 v156, v156
	v_mul_f32_e32 v149, 0x437f0000, v149
	v_rndne_f32_e32 v149, v149
	v_mul_f32_e32 v157, v157, v156
	v_mul_f32_e32 v157, 0x437f0000, v157
	v_rndne_f32_e32 v157, v157
	v_cvt_f16_f32_e32 v201, v157
	v_mul_f32_e32 v157, v153, v181
	v_rcp_f32_e32 v157, v157
	v_cvt_f16_f32_e32 v147, v147
	v_cvt_f16_f32_e32 v149, v149
	v_pk_mul_f32 v[152:153], v[152:153], v[156:157]
	s_nop 0
	v_pk_mul_f32 v[152:153], v[152:153], v[154:155]
	s_nop 0
	v_cvt_pk_f16_f32 v152, v152, v153
	v_mul_f32_e32 v153, v181, v157
	v_mul_f32_e32 v153, 0x437f0000, v153
	v_rndne_f32_e32 v153, v153
	v_cvt_f16_f32_e32 v153, v153
	v_pack_b32_f16 v154, v201, v152
	v_add_f32_e32 v157, v97, v129
	v_bfi_b32 v155, s98, v153, v152
	v_pack_b32_f16 v152, v147, v180
	v_add_f32_e32 v147, v100, v132
	v_bfi_b32 v153, s98, v149, v180
	v_med3_f32 v147, v147, s6, v191
	v_add_f32_e32 v149, v96, v128
	v_med3_f32 v149, v149, s6, v191
	v_mul_f32_e32 v147, 0xbfb8aa3b, v147
	v_exp_f32_e32 v156, v147
	v_mul_f32_e32 v147, 0xbfb8aa3b, v149
	v_add_f32_e32 v149, v101, v133
	v_med3_f32 v149, v149, s6, v191
	ds_write_b128 v158, v[152:155]
	v_lshlrev_b32_e32 v154, 16, v178
	v_and_b32_e32 v155, 0xffff0000, v178
	v_med3_f32 v178, v157, s6, v191
	v_mul_f32_e32 v149, 0xbfb8aa3b, v149
	v_exp_f32_e32 v157, v149
	v_mul_f32_e32 v149, 0xbfb8aa3b, v178
	v_exp_f32_e32 v147, v147
	v_exp_f32_e32 v149, v149
	v_pk_add_f32 v[156:157], v[156:157], 1.0 op_sel_hi:[1,0]
	v_lshlrev_b32_e32 v152, 16, v179
	v_add_f32_e32 v147, 1.0, v147
	v_add_f32_e32 v149, 1.0, v149
	v_and_b32_e32 v153, 0xffff0000, v179
	v_mul_f32_e32 v178, v156, v147
	v_mul_f32_e32 v179, v157, v149
	v_rcp_f32_e32 v178, v178
	v_rcp_f32_e32 v179, v179
	v_mul_f32_e32 v147, v147, v178
	v_pk_mul_f32 v[156:157], v[156:157], v[178:179]
	v_mul_f32_e32 v149, v149, v179
	v_pk_mul_f32 v[154:155], v[156:157], v[154:155]
	v_add_f32_e32 v156, v99, v131
	v_cvt_pk_f16_f32 v178, v154, v155
	v_add_f32_e32 v155, v98, v130
	v_med3_f32 v155, v155, s6, v191
	v_mul_f32_e32 v155, 0xbfb8aa3b, v155
	v_exp_f32_e32 v155, v155
	v_add_f32_e32 v154, v102, v134
	v_med3_f32 v154, v154, s6, v191
	v_mul_f32_e32 v154, 0xbfb8aa3b, v154
	v_add_f32_e32 v157, 1.0, v155
	v_add_f32_e32 v155, v103, v135
	v_med3_f32 v155, v155, s6, v191
	v_med3_f32 v156, v156, s6, v191
	v_mul_f32_e32 v155, 0xbfb8aa3b, v155
	v_exp_f32_e32 v154, v154
	v_exp_f32_e32 v155, v155
	v_mul_f32_e32 v156, 0xbfb8aa3b, v156
	v_exp_f32_e32 v156, v156
	v_mul_f32_e32 v147, 0x437f0000, v147
	v_pk_add_f32 v[154:155], v[154:155], 1.0 op_sel_hi:[1,0]
	v_rndne_f32_e32 v147, v147
	v_add_f32_e32 v179, 1.0, v156
	v_mul_f32_e32 v156, v154, v157
	v_rcp_f32_e32 v156, v156
	v_mul_f32_e32 v149, 0x437f0000, v149
	v_rndne_f32_e32 v149, v149
	v_mul_f32_e32 v157, v157, v156
	v_mul_f32_e32 v157, 0x437f0000, v157
	v_rndne_f32_e32 v157, v157
	v_cvt_f16_f32_e32 v180, v157
	v_mul_f32_e32 v157, v155, v179
	v_rcp_f32_e32 v157, v157
	v_cvt_f16_f32_e32 v147, v147
	v_cvt_f16_f32_e32 v149, v149
	v_pk_mul_f32 v[154:155], v[154:155], v[156:157]
	s_nop 0
	v_pk_mul_f32 v[152:153], v[154:155], v[152:153]
	s_nop 0
	v_cvt_pk_f16_f32 v152, v152, v153
	v_mul_f32_e32 v153, v179, v157
	v_mul_f32_e32 v153, 0x437f0000, v153
	v_rndne_f32_e32 v153, v153
	v_cvt_f16_f32_e32 v153, v153
	v_pack_b32_f16 v154, v180, v152
	v_add_f32_e32 v157, v81, v129
	v_bfi_b32 v155, s98, v153, v152
	v_pack_b32_f16 v152, v147, v178
	v_add_f32_e32 v147, v84, v132
	v_bfi_b32 v153, s98, v149, v178
	v_med3_f32 v147, v147, s6, v191
	v_add_f32_e32 v149, v80, v128
	v_med3_f32 v149, v149, s6, v191
	v_mul_f32_e32 v147, 0xbfb8aa3b, v147
	v_exp_f32_e32 v156, v147
	v_mul_f32_e32 v147, 0xbfb8aa3b, v149
	v_add_f32_e32 v149, v85, v133
	v_med3_f32 v149, v149, s6, v191
	ds_write_b128 v158, v[152:155] offset:4096
	v_lshlrev_b32_e32 v152, 16, v176
	v_and_b32_e32 v153, 0xffff0000, v176
	v_med3_f32 v176, v157, s6, v191
	v_mul_f32_e32 v149, 0xbfb8aa3b, v149
	v_exp_f32_e32 v157, v149
	v_mul_f32_e32 v149, 0xbfb8aa3b, v176
	v_exp_f32_e32 v147, v147
	v_exp_f32_e32 v149, v149
	v_pk_add_f32 v[156:157], v[156:157], 1.0 op_sel_hi:[1,0]
	v_lshlrev_b32_e32 v154, 16, v177
	v_add_f32_e32 v147, 1.0, v147
	v_add_f32_e32 v149, 1.0, v149
	v_and_b32_e32 v155, 0xffff0000, v177
	v_mul_f32_e32 v176, v156, v147
	v_mul_f32_e32 v177, v157, v149
	v_rcp_f32_e32 v176, v176
	v_rcp_f32_e32 v177, v177
	v_mul_f32_e32 v147, v147, v176
	v_pk_mul_f32 v[156:157], v[156:157], v[176:177]
	v_mul_f32_e32 v149, v149, v177
	v_pk_mul_f32 v[152:153], v[156:157], v[152:153]
	v_add_f32_e32 v156, v83, v131
	v_cvt_pk_f16_f32 v176, v152, v153
	v_add_f32_e32 v153, v82, v130
	v_med3_f32 v153, v153, s6, v191
	v_mul_f32_e32 v153, 0xbfb8aa3b, v153
	v_exp_f32_e32 v153, v153
	v_add_f32_e32 v152, v86, v134
	v_med3_f32 v152, v152, s6, v191
	v_mul_f32_e32 v152, 0xbfb8aa3b, v152
	v_add_f32_e32 v157, 1.0, v153
	v_add_f32_e32 v153, v87, v135
	v_med3_f32 v153, v153, s6, v191
	v_med3_f32 v156, v156, s6, v191
	v_mul_f32_e32 v153, 0xbfb8aa3b, v153
	v_exp_f32_e32 v152, v152
	v_exp_f32_e32 v153, v153
	v_mul_f32_e32 v156, 0xbfb8aa3b, v156
	v_exp_f32_e32 v156, v156
	v_mul_f32_e32 v147, 0x437f0000, v147
	v_pk_add_f32 v[152:153], v[152:153], 1.0 op_sel_hi:[1,0]
	v_rndne_f32_e32 v147, v147
	v_add_f32_e32 v177, 1.0, v156
	v_mul_f32_e32 v156, v152, v157
	v_rcp_f32_e32 v156, v156
	v_mul_f32_e32 v149, 0x437f0000, v149
	v_rndne_f32_e32 v149, v149
	v_mul_f32_e32 v157, v157, v156
	v_mul_f32_e32 v157, 0x437f0000, v157
	v_rndne_f32_e32 v157, v157
	v_cvt_f16_f32_e32 v178, v157
	v_mul_f32_e32 v157, v153, v177
	v_rcp_f32_e32 v157, v157
	v_cvt_f16_f32_e32 v147, v147
	v_cvt_f16_f32_e32 v149, v149
	v_pk_mul_f32 v[152:153], v[152:153], v[156:157]
	s_nop 0
	v_pk_mul_f32 v[152:153], v[152:153], v[154:155]
	s_nop 0
	v_cvt_pk_f16_f32 v152, v152, v153
	v_mul_f32_e32 v153, v177, v157
	v_mul_f32_e32 v153, 0x437f0000, v153
	v_rndne_f32_e32 v153, v153
	v_cvt_f16_f32_e32 v153, v153
	v_pack_b32_f16 v154, v178, v152
	v_add_f32_e32 v157, v65, v129
	v_bfi_b32 v155, s98, v153, v152
	v_pack_b32_f16 v152, v147, v176
	v_add_f32_e32 v147, v68, v132
	v_bfi_b32 v153, s98, v149, v176
	v_med3_f32 v147, v147, s6, v191
	v_add_f32_e32 v149, v64, v128
	v_med3_f32 v149, v149, s6, v191
	v_mul_f32_e32 v147, 0xbfb8aa3b, v147
	v_exp_f32_e32 v156, v147
	v_mul_f32_e32 v147, 0xbfb8aa3b, v149
	v_add_f32_e32 v149, v69, v133
	v_med3_f32 v149, v149, s6, v191
	ds_write_b128 v158, v[152:155] offset:8192
	v_lshlrev_b32_e32 v152, 16, v174
	v_and_b32_e32 v153, 0xffff0000, v174
	v_med3_f32 v174, v157, s6, v191
	v_mul_f32_e32 v149, 0xbfb8aa3b, v149
	v_exp_f32_e32 v157, v149
	v_mul_f32_e32 v149, 0xbfb8aa3b, v174
	v_exp_f32_e32 v147, v147
	v_exp_f32_e32 v149, v149
	v_pk_add_f32 v[156:157], v[156:157], 1.0 op_sel_hi:[1,0]
	v_lshlrev_b32_e32 v154, 16, v175
	v_add_f32_e32 v147, 1.0, v147
	v_add_f32_e32 v149, 1.0, v149
	v_and_b32_e32 v155, 0xffff0000, v175
	v_mul_f32_e32 v174, v156, v147
	v_mul_f32_e32 v175, v157, v149
	v_rcp_f32_e32 v174, v174
	v_rcp_f32_e32 v175, v175
	v_mul_f32_e32 v147, v147, v174
	v_pk_mul_f32 v[156:157], v[156:157], v[174:175]
	v_mul_f32_e32 v149, v149, v175
	v_pk_mul_f32 v[152:153], v[156:157], v[152:153]
	v_add_f32_e32 v156, v67, v131
	v_cvt_pk_f16_f32 v174, v152, v153
	v_add_f32_e32 v153, v66, v130
	v_med3_f32 v153, v153, s6, v191
	v_mul_f32_e32 v153, 0xbfb8aa3b, v153
	v_exp_f32_e32 v153, v153
	v_add_f32_e32 v152, v70, v134
	v_med3_f32 v152, v152, s6, v191
	v_mul_f32_e32 v152, 0xbfb8aa3b, v152
	v_add_f32_e32 v157, 1.0, v153
	v_add_f32_e32 v153, v71, v135
	v_med3_f32 v153, v153, s6, v191
	v_med3_f32 v156, v156, s6, v191
	v_mul_f32_e32 v153, 0xbfb8aa3b, v153
	v_exp_f32_e32 v152, v152
	v_exp_f32_e32 v153, v153
	v_mul_f32_e32 v156, 0xbfb8aa3b, v156
	v_exp_f32_e32 v156, v156
	v_mul_f32_e32 v147, 0x437f0000, v147
	v_pk_add_f32 v[152:153], v[152:153], 1.0 op_sel_hi:[1,0]
	v_rndne_f32_e32 v147, v147
	v_add_f32_e32 v175, 1.0, v156
	v_mul_f32_e32 v156, v152, v157
	v_rcp_f32_e32 v156, v156
	v_mul_f32_e32 v149, 0x437f0000, v149
	v_rndne_f32_e32 v149, v149
	v_mul_f32_e32 v157, v157, v156
	v_mul_f32_e32 v157, 0x437f0000, v157
	v_rndne_f32_e32 v157, v157
	v_cvt_f16_f32_e32 v176, v157
	v_mul_f32_e32 v157, v153, v175
	v_rcp_f32_e32 v157, v157
	v_cvt_f16_f32_e32 v147, v147
	v_cvt_f16_f32_e32 v149, v149
	v_pk_mul_f32 v[152:153], v[152:153], v[156:157]
	s_nop 0
	v_pk_mul_f32 v[152:153], v[152:153], v[154:155]
	s_nop 0
	v_cvt_pk_f16_f32 v152, v152, v153
	v_mul_f32_e32 v153, v175, v157
	v_mul_f32_e32 v153, 0x437f0000, v153
	v_rndne_f32_e32 v153, v153
	v_cvt_f16_f32_e32 v153, v153
	v_pack_b32_f16 v154, v176, v152
	v_add_f32_e32 v157, v49, v129
	v_bfi_b32 v155, s98, v153, v152
	v_pack_b32_f16 v152, v147, v174
	v_add_f32_e32 v147, v52, v132
	v_bfi_b32 v153, s98, v149, v174
	v_med3_f32 v147, v147, s6, v191
	v_add_f32_e32 v149, v48, v128
	v_med3_f32 v149, v149, s6, v191
	v_mul_f32_e32 v147, 0xbfb8aa3b, v147
	v_exp_f32_e32 v156, v147
	v_mul_f32_e32 v147, 0xbfb8aa3b, v149
	v_add_f32_e32 v149, v53, v133
	v_med3_f32 v149, v149, s6, v191
	ds_write_b128 v158, v[152:155] offset:12288
	v_lshlrev_b32_e32 v152, 16, v172
	v_and_b32_e32 v153, 0xffff0000, v172
	v_med3_f32 v172, v157, s6, v191
	v_mul_f32_e32 v149, 0xbfb8aa3b, v149
	v_exp_f32_e32 v157, v149
	v_mul_f32_e32 v149, 0xbfb8aa3b, v172
	v_exp_f32_e32 v147, v147
	v_exp_f32_e32 v149, v149
	v_pk_add_f32 v[156:157], v[156:157], 1.0 op_sel_hi:[1,0]
	v_lshlrev_b32_e32 v154, 16, v173
	v_add_f32_e32 v147, 1.0, v147
	v_add_f32_e32 v149, 1.0, v149
	v_and_b32_e32 v155, 0xffff0000, v173
	v_mul_f32_e32 v172, v156, v147
	v_mul_f32_e32 v173, v157, v149
	v_rcp_f32_e32 v172, v172
	v_rcp_f32_e32 v173, v173
	v_mul_f32_e32 v147, v147, v172
	v_pk_mul_f32 v[156:157], v[156:157], v[172:173]
	v_mul_f32_e32 v149, v149, v173
	v_pk_mul_f32 v[152:153], v[156:157], v[152:153]
	v_add_f32_e32 v156, v51, v131
	v_cvt_pk_f16_f32 v172, v152, v153
	v_add_f32_e32 v153, v50, v130
	v_med3_f32 v153, v153, s6, v191
	v_mul_f32_e32 v153, 0xbfb8aa3b, v153
	v_exp_f32_e32 v153, v153
	v_add_f32_e32 v152, v54, v134
	v_med3_f32 v152, v152, s6, v191
	v_mul_f32_e32 v152, 0xbfb8aa3b, v152
	v_add_f32_e32 v157, 1.0, v153
	v_add_f32_e32 v153, v55, v135
	v_med3_f32 v153, v153, s6, v191
	v_med3_f32 v156, v156, s6, v191
	v_mul_f32_e32 v153, 0xbfb8aa3b, v153
	v_exp_f32_e32 v152, v152
	v_exp_f32_e32 v153, v153
	v_mul_f32_e32 v156, 0xbfb8aa3b, v156
	v_exp_f32_e32 v156, v156
	v_mul_f32_e32 v147, 0x437f0000, v147
	v_pk_add_f32 v[152:153], v[152:153], 1.0 op_sel_hi:[1,0]
	v_rndne_f32_e32 v147, v147
	v_add_f32_e32 v173, 1.0, v156
	v_mul_f32_e32 v156, v152, v157
	v_rcp_f32_e32 v156, v156
	v_mul_f32_e32 v149, 0x437f0000, v149
	v_rndne_f32_e32 v149, v149
	v_mul_f32_e32 v157, v157, v156
	v_mul_f32_e32 v157, 0x437f0000, v157
	v_rndne_f32_e32 v157, v157
	v_cvt_f16_f32_e32 v174, v157
	v_mul_f32_e32 v157, v153, v173
	v_rcp_f32_e32 v157, v157
	v_cvt_f16_f32_e32 v147, v147
	v_cvt_f16_f32_e32 v149, v149
	v_pk_mul_f32 v[152:153], v[152:153], v[156:157]
	s_nop 0
	v_pk_mul_f32 v[152:153], v[152:153], v[154:155]
	s_nop 0
	v_cvt_pk_f16_f32 v152, v152, v153
	v_mul_f32_e32 v153, v173, v157
	v_mul_f32_e32 v153, 0x437f0000, v153
	v_rndne_f32_e32 v153, v153
	v_cvt_f16_f32_e32 v153, v153
	v_pack_b32_f16 v154, v174, v152
	v_add_f32_e32 v157, v33, v129
	v_bfi_b32 v155, s98, v153, v152
	v_pack_b32_f16 v152, v147, v172
	v_add_f32_e32 v147, v36, v132
	v_bfi_b32 v153, s98, v149, v172
	v_med3_f32 v147, v147, s6, v191
	v_add_f32_e32 v149, v32, v128
	v_med3_f32 v149, v149, s6, v191
	v_mul_f32_e32 v147, 0xbfb8aa3b, v147
	v_exp_f32_e32 v156, v147
	v_mul_f32_e32 v147, 0xbfb8aa3b, v149
	v_add_f32_e32 v149, v37, v133
	v_med3_f32 v149, v149, s6, v191
	ds_write_b128 v158, v[152:155] offset:16384
	v_lshlrev_b32_e32 v152, 16, v170
	v_and_b32_e32 v153, 0xffff0000, v170
	v_med3_f32 v170, v157, s6, v191
	v_mul_f32_e32 v149, 0xbfb8aa3b, v149
	v_exp_f32_e32 v157, v149
	v_mul_f32_e32 v149, 0xbfb8aa3b, v170
	v_exp_f32_e32 v147, v147
	v_exp_f32_e32 v149, v149
	v_pk_add_f32 v[156:157], v[156:157], 1.0 op_sel_hi:[1,0]
	v_lshlrev_b32_e32 v154, 16, v171
	v_add_f32_e32 v147, 1.0, v147
	v_add_f32_e32 v149, 1.0, v149
	v_and_b32_e32 v155, 0xffff0000, v171
	v_mul_f32_e32 v170, v156, v147
	v_mul_f32_e32 v171, v157, v149
	v_rcp_f32_e32 v170, v170
	v_rcp_f32_e32 v171, v171
	v_mul_f32_e32 v147, v147, v170
	v_pk_mul_f32 v[156:157], v[156:157], v[170:171]
	v_mul_f32_e32 v149, v149, v171
	v_pk_mul_f32 v[152:153], v[156:157], v[152:153]
	v_add_f32_e32 v156, v35, v131
	v_cvt_pk_f16_f32 v170, v152, v153
	v_add_f32_e32 v153, v34, v130
	v_med3_f32 v153, v153, s6, v191
	v_mul_f32_e32 v153, 0xbfb8aa3b, v153
	v_exp_f32_e32 v153, v153
	v_add_f32_e32 v152, v38, v134
	v_med3_f32 v152, v152, s6, v191
	v_mul_f32_e32 v152, 0xbfb8aa3b, v152
	v_add_f32_e32 v157, 1.0, v153
	v_add_f32_e32 v153, v39, v135
	v_med3_f32 v153, v153, s6, v191
	v_med3_f32 v156, v156, s6, v191
	v_mul_f32_e32 v153, 0xbfb8aa3b, v153
	v_exp_f32_e32 v152, v152
	v_exp_f32_e32 v153, v153
	v_mul_f32_e32 v156, 0xbfb8aa3b, v156
	v_exp_f32_e32 v156, v156
	v_mul_f32_e32 v147, 0x437f0000, v147
	v_pk_add_f32 v[152:153], v[152:153], 1.0 op_sel_hi:[1,0]
	v_rndne_f32_e32 v147, v147
	v_add_f32_e32 v171, 1.0, v156
	v_mul_f32_e32 v156, v152, v157
	v_rcp_f32_e32 v156, v156
	v_mul_f32_e32 v149, 0x437f0000, v149
	v_rndne_f32_e32 v149, v149
	v_mul_f32_e32 v157, v157, v156
	v_mul_f32_e32 v157, 0x437f0000, v157
	v_rndne_f32_e32 v157, v157
	v_cvt_f16_f32_e32 v172, v157
	v_mul_f32_e32 v157, v153, v171
	v_rcp_f32_e32 v157, v157
	v_cvt_f16_f32_e32 v147, v147
	v_cvt_f16_f32_e32 v149, v149
	v_pk_mul_f32 v[152:153], v[152:153], v[156:157]
	s_nop 0
	v_pk_mul_f32 v[152:153], v[152:153], v[154:155]
	s_nop 0
	v_cvt_pk_f16_f32 v152, v152, v153
	v_mul_f32_e32 v153, v171, v157
	v_mul_f32_e32 v153, 0x437f0000, v153
	v_rndne_f32_e32 v153, v153
	v_cvt_f16_f32_e32 v153, v153
	v_pack_b32_f16 v154, v172, v152
	v_add_f32_e32 v157, v17, v129
	v_add_f32_e32 v129, v1, v129
	v_bfi_b32 v155, s98, v153, v152
	v_pack_b32_f16 v152, v147, v170
	v_add_f32_e32 v147, v20, v132
	v_bfi_b32 v153, s98, v149, v170
	v_med3_f32 v147, v147, s6, v191
	v_add_f32_e32 v149, v16, v128
	v_med3_f32 v149, v149, s6, v191
	v_mul_f32_e32 v147, 0xbfb8aa3b, v147
	v_exp_f32_e32 v156, v147
	v_mul_f32_e32 v147, 0xbfb8aa3b, v149
	v_add_f32_e32 v149, v21, v133
	v_med3_f32 v149, v149, s6, v191
	ds_write_b128 v158, v[152:155] offset:20480
	v_lshlrev_b32_e32 v152, 16, v168
	v_and_b32_e32 v153, 0xffff0000, v168
	v_med3_f32 v168, v157, s6, v191
	v_mul_f32_e32 v149, 0xbfb8aa3b, v149
	v_exp_f32_e32 v157, v149
	v_mul_f32_e32 v149, 0xbfb8aa3b, v168
	v_exp_f32_e32 v147, v147
	v_exp_f32_e32 v149, v149
	v_pk_add_f32 v[156:157], v[156:157], 1.0 op_sel_hi:[1,0]
	v_lshlrev_b32_e32 v154, 16, v169
	v_add_f32_e32 v147, 1.0, v147
	v_add_f32_e32 v149, 1.0, v149
	v_and_b32_e32 v155, 0xffff0000, v169
	v_mul_f32_e32 v168, v156, v147
	v_mul_f32_e32 v169, v157, v149
	v_rcp_f32_e32 v168, v168
	v_rcp_f32_e32 v169, v169
	v_add_f32_e32 v132, v4, v132
	v_add_f32_e32 v128, v0, v128
	v_mul_f32_e32 v147, v147, v168
	v_pk_mul_f32 v[156:157], v[156:157], v[168:169]
	v_mul_f32_e32 v149, v149, v169
	v_pk_mul_f32 v[152:153], v[156:157], v[152:153]
	v_add_f32_e32 v156, v19, v131
	v_cvt_pk_f16_f32 v168, v152, v153
	v_add_f32_e32 v153, v18, v130
	v_med3_f32 v153, v153, s6, v191
	v_mul_f32_e32 v153, 0xbfb8aa3b, v153
	v_exp_f32_e32 v153, v153
	v_add_f32_e32 v152, v22, v134
	v_med3_f32 v152, v152, s6, v191
	v_mul_f32_e32 v152, 0xbfb8aa3b, v152
	v_add_f32_e32 v157, 1.0, v153
	v_add_f32_e32 v153, v23, v135
	v_med3_f32 v153, v153, s6, v191
	v_med3_f32 v156, v156, s6, v191
	v_mul_f32_e32 v153, 0xbfb8aa3b, v153
	v_exp_f32_e32 v152, v152
	v_exp_f32_e32 v153, v153
	v_mul_f32_e32 v156, 0xbfb8aa3b, v156
	v_exp_f32_e32 v156, v156
	v_mul_f32_e32 v147, 0x437f0000, v147
	v_pk_add_f32 v[152:153], v[152:153], 1.0 op_sel_hi:[1,0]
	v_rndne_f32_e32 v147, v147
	v_add_f32_e32 v169, 1.0, v156
	v_mul_f32_e32 v156, v152, v157
	v_rcp_f32_e32 v156, v156
	v_cvt_f16_f32_e32 v147, v147
	v_med3_f32 v132, v132, s6, v191
	v_mul_f32_e32 v157, v157, v156
	v_mul_f32_e32 v157, 0x437f0000, v157
	v_rndne_f32_e32 v157, v157
	v_cvt_f16_f32_e32 v170, v157
	v_mul_f32_e32 v157, v153, v169
	v_rcp_f32_e32 v157, v157
	v_mul_f32_e32 v149, 0x437f0000, v149
	v_rndne_f32_e32 v149, v149
	v_pk_mul_f32 v[152:153], v[152:153], v[156:157]
	v_cvt_f16_f32_e32 v149, v149
	v_pk_mul_f32 v[152:153], v[152:153], v[154:155]
	s_nop 0
	v_cvt_pk_f16_f32 v152, v152, v153
	v_mul_f32_e32 v153, v169, v157
	v_mul_f32_e32 v153, 0x437f0000, v153
	v_rndne_f32_e32 v153, v153
	v_cvt_f16_f32_e32 v153, v153
	v_pack_b32_f16 v154, v170, v152
	v_bfi_b32 v155, s98, v153, v152
	v_pack_b32_f16 v152, v147, v168
	v_med3_f32 v147, v128, s6, v191
	v_mul_f32_e32 v128, 0xbfb8aa3b, v132
	v_mul_f32_e32 v132, 0xbfb8aa3b, v147
	v_exp_f32_e32 v132, v132
	v_exp_f32_e32 v128, v128
	v_bfi_b32 v153, s98, v149, v168
	ds_write_b128 v158, v[152:155] offset:24576
	v_add_f32_e32 v147, 1.0, v132
	v_add_f32_e32 v132, v5, v133
	v_med3_f32 v132, v132, s6, v191
	v_med3_f32 v133, v129, s6, v191
	v_mul_f32_e32 v129, 0xbfb8aa3b, v132
	v_exp_f32_e32 v129, v129
	v_mul_f32_e32 v132, 0xbfb8aa3b, v133
	v_exp_f32_e32 v132, v132
	v_lshlrev_b32_e32 v152, 16, v166
	v_pk_add_f32 v[128:129], v[128:129], 1.0 op_sel_hi:[1,0]
	v_and_b32_e32 v153, 0xffff0000, v166
	v_add_f32_e32 v149, 1.0, v132
	v_mul_f32_e32 v132, v128, v147
	v_rcp_f32_e32 v132, v132
	v_lshlrev_b32_e32 v154, 16, v167
	v_and_b32_e32 v155, 0xffff0000, v167
	v_mul_f32_e32 v133, v147, v132
	v_mul_f32_e32 v133, 0x437f0000, v133
	v_rndne_f32_e32 v133, v133
	v_cvt_f16_f32_e32 v147, v133
	v_mul_f32_e32 v133, v129, v149
	v_rcp_f32_e32 v133, v133
	s_nop 0
	v_pk_mul_f32 v[128:129], v[128:129], v[132:133]
	s_nop 0
	v_pk_mul_f32 v[128:129], v[128:129], v[152:153]
	s_nop 0
	v_cvt_pk_f16_f32 v132, v128, v129
	v_add_f32_e32 v129, v2, v130
	v_med3_f32 v129, v129, s6, v191
	v_mul_f32_e32 v129, 0xbfb8aa3b, v129
	v_mul_f32_e32 v128, v149, v133
	v_exp_f32_e32 v129, v129
	v_mul_f32_e32 v128, 0x437f0000, v128
	v_rndne_f32_e32 v128, v128
	v_cvt_f16_f32_e32 v133, v128
	v_add_f32_e32 v128, v6, v134
	v_add_f32_e32 v134, 1.0, v129
	v_add_f32_e32 v129, v7, v135
	v_med3_f32 v128, v128, s6, v191
	v_med3_f32 v129, v129, s6, v191
	v_add_f32_e32 v130, v3, v131
	v_mul_f32_e32 v128, 0xbfb8aa3b, v128
	v_med3_f32 v130, v130, s6, v191
	v_mul_f32_e32 v129, 0xbfb8aa3b, v129
	v_exp_f32_e32 v128, v128
	v_exp_f32_e32 v129, v129
	v_mul_f32_e32 v130, 0xbfb8aa3b, v130
	v_exp_f32_e32 v130, v130
	v_pk_add_f32 v[128:129], v[128:129], 1.0 op_sel_hi:[1,0]
	v_add_f32_e32 v135, 1.0, v130
	v_mul_f32_e32 v130, v128, v134
	v_rcp_f32_e32 v130, v130
	s_nop 0
	v_mul_f32_e32 v131, v134, v130
	v_mul_f32_e32 v131, 0x437f0000, v131
	v_rndne_f32_e32 v131, v131
	v_cvt_f16_f32_e32 v134, v131
	v_mul_f32_e32 v131, v129, v135
	v_rcp_f32_e32 v131, v131
	s_nop 0
	v_pk_mul_f32 v[128:129], v[128:129], v[130:131]
	s_nop 0
	v_pk_mul_f32 v[128:129], v[128:129], v[154:155]
	v_mov_b32_e32 v155, v164
	v_cvt_pk_f16_f32 v128, v128, v129
	v_mul_f32_e32 v129, v135, v131
	v_mul_f32_e32 v129, 0x437f0000, v129
	v_rndne_f32_e32 v129, v129
	v_cvt_f16_f32_e32 v129, v129
	v_pack_b32_f16 v130, v134, v128
	v_ashrrev_i32_e32 v134, 3, v200
	v_bfi_b32 v131, s98, v129, v128
	v_bfi_b32 v129, s98, v133, v132
	v_pack_b32_f16 v128, v147, v132
	v_and_b32_e32 v147, 7, v200
	ds_write_b128 v158, v[128:131] offset:28672
	v_lshlrev_b32_e32 v129, 1, v147
	v_lshl_add_u32 v128, v134, 8, v192
	v_and_b32_e32 v130, 15, v134
	v_bitop3_b32 v131, v129, v134, 15 bitop3:0x78
	v_lshl_or_b32 v131, v131, 4, v128
	v_bitop3_b32 v129, v129, v130, 1 bitop3:0x36
	s_waitcnt lgkmcnt(0)
	s_barrier
	v_lshl_or_b32 v132, v129, 4, v128
	ds_read_b128 v[128:131], v131
	s_waitcnt lgkmcnt(0)
	v_and_b32_e32 v135, 0xffff0000, v129
	v_cvt_f32_f16_e32 v149, v128
	v_cvt_f32_f16_e32 v129, v129
	v_and_b32_e32 v133, 0xffff0000, v131
	v_cvt_f32_f16_e32 v152, v130
	v_cvt_f32_f16_e32 v131, v131
	v_cvt_u32_f32_e32 v149, v149
	v_cvt_u32_f32_e32 v129, v129
	v_cvt_u32_f32_sdwa v152, v152 dst_sel:WORD_1 dst_unused:UNUSED_PAD src0_sel:DWORD
	v_cvt_u32_f32_sdwa v131, v131 dst_sel:BYTE_3 dst_unused:UNUSED_PAD src0_sel:DWORD
	v_or_b32_sdwa v128, v135, v128 dst_sel:DWORD dst_unused:UNUSED_PAD src0_sel:DWORD src1_sel:WORD_1
	v_lshl_or_b32 v129, v129, 8, v149
	v_or3_b32 v152, v129, v152, v131
	v_or_b32_sdwa v129, v133, v130 dst_sel:DWORD dst_unused:UNUSED_PAD src0_sel:DWORD src1_sel:WORD_1
	ds_read_b128 v[130:133], v132
	s_waitcnt lgkmcnt(0)
	v_and_b32_e32 v149, 0xffff0000, v131
	v_cvt_f32_f16_e32 v153, v130
	v_cvt_f32_f16_e32 v131, v131
	v_and_b32_e32 v135, 0xffff0000, v133
	v_cvt_f32_f16_e32 v154, v132
	v_cvt_f32_f16_e32 v133, v133
	v_cvt_u32_f32_e32 v153, v153
	v_cvt_u32_f32_e32 v131, v131
	v_cvt_u32_f32_sdwa v154, v154 dst_sel:WORD_1 dst_unused:UNUSED_PAD src0_sel:DWORD
	v_cvt_u32_f32_sdwa v133, v133 dst_sel:BYTE_3 dst_unused:UNUSED_PAD src0_sel:DWORD
	v_or_b32_sdwa v130, v149, v130 dst_sel:DWORD dst_unused:UNUSED_PAD src0_sel:DWORD src1_sel:WORD_1
	v_lshl_or_b32 v131, v131, 8, v153
	v_or3_b32 v153, v131, v154, v133
	v_or_b32_sdwa v131, v135, v132 dst_sel:DWORD dst_unused:UNUSED_PAD src0_sel:DWORD src1_sel:WORD_1
	v_ashrrev_i32_e32 v135, 31, v134
	v_lshlrev_b64 v[132:133], 10, v[134:135]
	v_lshl_add_u64 v[132:133], s[12:13], 0, v[132:133]
	v_lshlrev_b32_e32 v154, 3, v147
	v_lshl_add_u64 v[132:133], v[132:133], 0, v[154:155]
	global_store_dwordx2 v[132:133], v[152:153], off offset:64
	v_lshlrev_b32_e32 v132, 4, v147
	v_lshl_or_b32 v132, v134, 11, v132
	buffer_store_dwordx4 v[128:131], v132, s[8:11], 0 offen offset:128 sc1
	s_nop 1
	v_add_u32_e32 v128, v197, v199
	ds_read_b128 v[128:131], v128
	s_waitcnt lgkmcnt(0)
	v_and_b32_e32 v133, 0xffff0000, v129
	v_cvt_f32_f16_e32 v134, v128
	v_cvt_f32_f16_e32 v129, v129
	v_and_b32_e32 v132, 0xffff0000, v131
	v_cvt_f32_f16_e32 v135, v130
	v_cvt_f32_f16_e32 v131, v131
	v_cvt_u32_f32_e32 v134, v134
	v_cvt_u32_f32_e32 v129, v129
	v_cvt_u32_f32_sdwa v135, v135 dst_sel:WORD_1 dst_unused:UNUSED_PAD src0_sel:DWORD
	v_cvt_u32_f32_sdwa v131, v131 dst_sel:BYTE_3 dst_unused:UNUSED_PAD src0_sel:DWORD
	v_or_b32_sdwa v128, v133, v128 dst_sel:DWORD dst_unused:UNUSED_PAD src0_sel:DWORD src1_sel:WORD_1
	v_lshl_or_b32 v129, v129, 8, v134
	v_or3_b32 v134, v129, v135, v131
	v_or_b32_sdwa v129, v132, v130 dst_sel:DWORD dst_unused:UNUSED_PAD src0_sel:DWORD src1_sel:WORD_1
	v_add_u32_e32 v130, v197, v198
	ds_read_b128 v[130:133], v130
	s_waitcnt lgkmcnt(0)
	v_and_b32_e32 v149, 0xffff0000, v131
	v_cvt_f32_f16_e32 v135, v130
	v_cvt_f32_f16_e32 v131, v131
	v_and_b32_e32 v147, 0xffff0000, v133
	v_cvt_f32_f16_e32 v152, v132
	v_cvt_f32_f16_e32 v133, v133
	v_cvt_u32_f32_e32 v135, v135
	v_cvt_u32_f32_e32 v131, v131
	v_cvt_u32_f32_sdwa v152, v152 dst_sel:WORD_1 dst_unused:UNUSED_PAD src0_sel:DWORD
	v_cvt_u32_f32_sdwa v133, v133 dst_sel:BYTE_3 dst_unused:UNUSED_PAD src0_sel:DWORD
	v_or_b32_sdwa v130, v149, v130 dst_sel:DWORD dst_unused:UNUSED_PAD src0_sel:DWORD src1_sel:WORD_1
	v_lshl_or_b32 v131, v131, 8, v135
	v_or3_b32 v135, v131, v152, v133
	v_or_b32_sdwa v131, v147, v132 dst_sel:DWORD dst_unused:UNUSED_PAD src0_sel:DWORD src1_sel:WORD_1
	global_store_dwordx2 v[150:151], v[134:135], off offset:64
	buffer_store_dwordx4 v[128:131], v196, s[8:11], 0 offen offset:128 sc1
	s_and_saveexec_b64 s[4:5], vcc
	s_xor_b64 s[4:5], exec, s[4:5]
	s_cbranch_execz .LBB0_465
	v_lshl_add_u32 v129, v148, 8, v192
	v_bitop3_b32 v128, v148, v160, 15 bitop3:0x6c
	v_lshl_or_b32 v130, v128, 4, v129
	v_or_b32_e32 v128, 1, v160
	v_bitop3_b32 v131, v148, v128, 15 bitop3:0x6c
	v_lshl_or_b32 v129, v131, 4, v129
	ds_read_b128 v[130:133], v130
	v_ashrrev_i32_e32 v149, 31, v148
	v_mov_b32_e32 v141, v164
	v_ashrrev_i32_e32 v147, 31, v146
	v_ashrrev_i32_e32 v145, 31, v144
	s_waitcnt lgkmcnt(0)
	v_and_b32_e32 v135, 0xffff0000, v131
	v_cvt_f32_f16_e32 v136, v130
	v_cvt_f32_f16_e32 v131, v131
	v_and_b32_e32 v134, 0xffff0000, v133
	v_cvt_f32_f16_e32 v137, v132
	v_cvt_f32_f16_e32 v133, v133
	v_cvt_u32_f32_e32 v136, v136
	v_cvt_u32_f32_e32 v131, v131
	v_cvt_u32_f32_sdwa v137, v137 dst_sel:WORD_1 dst_unused:UNUSED_PAD src0_sel:DWORD
	v_cvt_u32_f32_sdwa v133, v133 dst_sel:BYTE_3 dst_unused:UNUSED_PAD src0_sel:DWORD
	v_or_b32_sdwa v130, v135, v130 dst_sel:DWORD dst_unused:UNUSED_PAD src0_sel:DWORD src1_sel:WORD_1
	v_lshl_or_b32 v131, v131, 8, v136
	v_ashrrev_i32_e32 v143, 31, v142
	v_or3_b32 v136, v131, v137, v133
	v_or_b32_sdwa v131, v134, v132 dst_sel:DWORD dst_unused:UNUSED_PAD src0_sel:DWORD src1_sel:WORD_1
	ds_read_b128 v[132:135], v129
	s_waitcnt lgkmcnt(0)
	v_and_b32_e32 v138, 0xffff0000, v133
	v_cvt_f32_f16_e32 v137, v132
	v_cvt_f32_f16_e32 v133, v133
	v_and_b32_e32 v129, 0xffff0000, v135
	v_cvt_f32_f16_e32 v139, v134
	v_cvt_f32_f16_e32 v135, v135
	v_cvt_u32_f32_e32 v137, v137
	v_cvt_u32_f32_e32 v133, v133
	v_cvt_u32_f32_sdwa v139, v139 dst_sel:WORD_1 dst_unused:UNUSED_PAD src0_sel:DWORD
	v_cvt_u32_f32_sdwa v135, v135 dst_sel:BYTE_3 dst_unused:UNUSED_PAD src0_sel:DWORD
	v_or_b32_sdwa v132, v138, v132 dst_sel:DWORD dst_unused:UNUSED_PAD src0_sel:DWORD src1_sel:WORD_1
	v_lshl_or_b32 v133, v133, 8, v137
	v_or3_b32 v137, v133, v139, v135
	v_or_b32_sdwa v133, v129, v134 dst_sel:DWORD dst_unused:UNUSED_PAD src0_sel:DWORD src1_sel:WORD_1
	v_lshlrev_b64 v[134:135], 10, v[148:149]
	v_lshl_add_u64 v[134:135], s[12:13], 0, v[134:135]
	v_lshl_add_u64 v[134:135], v[134:135], 0, v[140:141]
	v_lshl_or_b32 v129, v148, 11, v159
	global_store_dwordx2 v[134:135], v[136:137], off offset:64
	buffer_store_dwordx4 v[130:133], v129, s[8:11], 0 offen offset:128 sc1
	v_lshl_add_u32 v129, v146, 8, v192
	s_nop 0
	v_bitop3_b32 v130, v146, v160, 15 bitop3:0x6c
	v_lshl_or_b32 v130, v130, 4, v129
	v_bitop3_b32 v131, v146, v128, 15 bitop3:0x6c
	v_lshl_or_b32 v129, v131, 4, v129
	ds_read_b128 v[130:133], v130
	s_waitcnt lgkmcnt(0)
	v_and_b32_e32 v135, 0xffff0000, v131
	v_cvt_f32_f16_e32 v136, v130
	v_cvt_f32_f16_e32 v131, v131
	v_and_b32_e32 v134, 0xffff0000, v133
	v_cvt_f32_f16_e32 v137, v132
	v_cvt_f32_f16_e32 v133, v133
	v_cvt_u32_f32_e32 v136, v136
	v_cvt_u32_f32_e32 v131, v131
	v_cvt_u32_f32_sdwa v137, v137 dst_sel:WORD_1 dst_unused:UNUSED_PAD src0_sel:DWORD
	v_cvt_u32_f32_sdwa v133, v133 dst_sel:BYTE_3 dst_unused:UNUSED_PAD src0_sel:DWORD
	v_or_b32_sdwa v130, v135, v130 dst_sel:DWORD dst_unused:UNUSED_PAD src0_sel:DWORD src1_sel:WORD_1
	v_lshl_or_b32 v131, v131, 8, v136
	v_or3_b32 v136, v131, v137, v133
	v_or_b32_sdwa v131, v134, v132 dst_sel:DWORD dst_unused:UNUSED_PAD src0_sel:DWORD src1_sel:WORD_1
	ds_read_b128 v[132:135], v129
	s_waitcnt lgkmcnt(0)
	v_and_b32_e32 v138, 0xffff0000, v133
	v_cvt_f32_f16_e32 v137, v132
	v_cvt_f32_f16_e32 v133, v133
	v_and_b32_e32 v129, 0xffff0000, v135
	v_cvt_f32_f16_e32 v139, v134
	v_cvt_f32_f16_e32 v135, v135
	v_cvt_u32_f32_e32 v137, v137
	v_cvt_u32_f32_e32 v133, v133
	v_cvt_u32_f32_sdwa v139, v139 dst_sel:WORD_1 dst_unused:UNUSED_PAD src0_sel:DWORD
	v_cvt_u32_f32_sdwa v135, v135 dst_sel:BYTE_3 dst_unused:UNUSED_PAD src0_sel:DWORD
	v_or_b32_sdwa v132, v138, v132 dst_sel:DWORD dst_unused:UNUSED_PAD src0_sel:DWORD src1_sel:WORD_1
	v_lshl_or_b32 v133, v133, 8, v137
	v_or3_b32 v137, v133, v139, v135
	v_or_b32_sdwa v133, v129, v134 dst_sel:DWORD dst_unused:UNUSED_PAD src0_sel:DWORD src1_sel:WORD_1
	v_lshlrev_b64 v[134:135], 10, v[146:147]
	v_lshl_add_u64 v[134:135], s[12:13], 0, v[134:135]
	v_lshl_add_u64 v[134:135], v[134:135], 0, v[140:141]
	v_lshl_or_b32 v129, v146, 11, v159
	global_store_dwordx2 v[134:135], v[136:137], off offset:64
	buffer_store_dwordx4 v[130:133], v129, s[8:11], 0 offen offset:128 sc1
	v_lshl_add_u32 v129, v144, 8, v192
	s_nop 0
	v_bitop3_b32 v130, v144, v160, 15 bitop3:0x6c
	v_lshl_or_b32 v130, v130, 4, v129
	v_bitop3_b32 v131, v144, v128, 15 bitop3:0x6c
	v_lshl_or_b32 v129, v131, 4, v129
	ds_read_b128 v[130:133], v130
	v_bitop3_b32 v128, v142, v128, 15 bitop3:0x6c
	s_waitcnt lgkmcnt(0)
	v_and_b32_e32 v135, 0xffff0000, v131
	v_cvt_f32_f16_e32 v136, v130
	v_cvt_f32_f16_e32 v131, v131
	v_and_b32_e32 v134, 0xffff0000, v133
	v_cvt_f32_f16_e32 v137, v132
	v_cvt_f32_f16_e32 v133, v133
	v_cvt_u32_f32_e32 v136, v136
	v_cvt_u32_f32_e32 v131, v131
	v_cvt_u32_f32_sdwa v137, v137 dst_sel:WORD_1 dst_unused:UNUSED_PAD src0_sel:DWORD
	v_cvt_u32_f32_sdwa v133, v133 dst_sel:BYTE_3 dst_unused:UNUSED_PAD src0_sel:DWORD
	v_or_b32_sdwa v130, v135, v130 dst_sel:DWORD dst_unused:UNUSED_PAD src0_sel:DWORD src1_sel:WORD_1
	v_lshl_or_b32 v131, v131, 8, v136
	v_or3_b32 v136, v131, v137, v133
	v_or_b32_sdwa v131, v134, v132 dst_sel:DWORD dst_unused:UNUSED_PAD src0_sel:DWORD src1_sel:WORD_1
	ds_read_b128 v[132:135], v129
	s_waitcnt lgkmcnt(0)
	v_and_b32_e32 v138, 0xffff0000, v133
	v_cvt_f32_f16_e32 v137, v132
	v_cvt_f32_f16_e32 v133, v133
	v_and_b32_e32 v129, 0xffff0000, v135
	v_cvt_f32_f16_e32 v139, v134
	v_cvt_f32_f16_e32 v135, v135
	v_cvt_u32_f32_e32 v137, v137
	v_cvt_u32_f32_e32 v133, v133
	v_cvt_u32_f32_sdwa v139, v139 dst_sel:WORD_1 dst_unused:UNUSED_PAD src0_sel:DWORD
	v_cvt_u32_f32_sdwa v135, v135 dst_sel:BYTE_3 dst_unused:UNUSED_PAD src0_sel:DWORD
	v_or_b32_sdwa v132, v138, v132 dst_sel:DWORD dst_unused:UNUSED_PAD src0_sel:DWORD src1_sel:WORD_1
	v_lshl_or_b32 v133, v133, 8, v137
	v_or3_b32 v137, v133, v139, v135
	v_or_b32_sdwa v133, v129, v134 dst_sel:DWORD dst_unused:UNUSED_PAD src0_sel:DWORD src1_sel:WORD_1
	v_lshlrev_b64 v[134:135], 10, v[144:145]
	v_lshl_add_u64 v[134:135], s[12:13], 0, v[134:135]
	v_lshl_add_u64 v[134:135], v[134:135], 0, v[140:141]
	v_lshl_or_b32 v129, v144, 11, v159
	global_store_dwordx2 v[134:135], v[136:137], off offset:64
	buffer_store_dwordx4 v[130:133], v129, s[8:11], 0 offen offset:128 sc1
	v_lshl_add_u32 v129, v142, 8, v192
	s_nop 0
	v_bitop3_b32 v130, v142, v160, 15 bitop3:0x6c
	v_lshl_or_b32 v130, v130, 4, v129
	v_lshl_or_b32 v132, v128, 4, v129
	ds_read_b128 v[128:131], v130
	s_waitcnt lgkmcnt(0)
	v_and_b32_e32 v135, 0xffff0000, v129
	v_cvt_f32_f16_e32 v134, v128
	v_cvt_f32_f16_e32 v129, v129
	v_and_b32_e32 v133, 0xffff0000, v131
	v_cvt_f32_f16_e32 v136, v130
	v_cvt_f32_f16_e32 v131, v131
	v_cvt_u32_f32_e32 v134, v134
	v_cvt_u32_f32_e32 v129, v129
	v_cvt_u32_f32_sdwa v136, v136 dst_sel:WORD_1 dst_unused:UNUSED_PAD src0_sel:DWORD
	v_cvt_u32_f32_sdwa v131, v131 dst_sel:BYTE_3 dst_unused:UNUSED_PAD src0_sel:DWORD
	v_or_b32_sdwa v128, v135, v128 dst_sel:DWORD dst_unused:UNUSED_PAD src0_sel:DWORD src1_sel:WORD_1
	v_lshl_or_b32 v129, v129, 8, v134
	v_or3_b32 v134, v129, v136, v131
	v_or_b32_sdwa v129, v133, v130 dst_sel:DWORD dst_unused:UNUSED_PAD src0_sel:DWORD src1_sel:WORD_1
	ds_read_b128 v[130:133], v132
	s_waitcnt lgkmcnt(0)
	v_and_b32_e32 v137, 0xffff0000, v131
	v_cvt_f32_f16_e32 v135, v130
	v_cvt_f32_f16_e32 v131, v131
	v_and_b32_e32 v136, 0xffff0000, v133
	v_cvt_f32_f16_e32 v138, v132
	v_cvt_f32_f16_e32 v133, v133
	v_cvt_u32_f32_e32 v135, v135
	v_cvt_u32_f32_e32 v131, v131
	v_cvt_u32_f32_sdwa v138, v138 dst_sel:WORD_1 dst_unused:UNUSED_PAD src0_sel:DWORD
	v_cvt_u32_f32_sdwa v133, v133 dst_sel:BYTE_3 dst_unused:UNUSED_PAD src0_sel:DWORD
	v_or_b32_sdwa v130, v137, v130 dst_sel:DWORD dst_unused:UNUSED_PAD src0_sel:DWORD src1_sel:WORD_1
	v_lshl_or_b32 v131, v131, 8, v135
	v_or3_b32 v135, v131, v138, v133
	v_or_b32_sdwa v131, v136, v132 dst_sel:DWORD dst_unused:UNUSED_PAD src0_sel:DWORD src1_sel:WORD_1
	v_lshlrev_b64 v[132:133], 10, v[142:143]
	v_lshl_add_u64 v[132:133], s[12:13], 0, v[132:133]
	v_lshl_add_u64 v[132:133], v[132:133], 0, v[140:141]
	global_store_dwordx2 v[132:133], v[134:135], off offset:64
	v_lshl_or_b32 v132, v142, 11, v159
	buffer_store_dwordx4 v[128:131], v132, s[8:11], 0 offen offset:128 sc1
